# all prompt GEMM K-loops: stage LDS-DMA loads issued at the top of each load segment, fragment ds_reads after them
# baseline (speedup 1.0000x reference)
.LBB0_117:
	s_add_u32 s50, s48, 0xfff80080
	s_addc_u32 s51, s49, -1
	s_cmp_eq_u32 s74, 28
	s_cselect_b32 s53, s9, s51
	s_cselect_b32 s52, s43, s50
	s_cselect_b32 s51, s41, s73
	s_cselect_b32 s50, s71, s72
	v_lshl_add_u64 v[154:155], s[48:49], 0, v[146:147]
	s_add_i32 m0, s56, 0xc000
	s_nop 0
	global_load_lds_dwordx4 v[154:155], off
	v_lshl_add_u64 v[154:155], s[48:49], 0, v[148:149]
	s_add_i32 m0, s56, 0xe000
	s_nop 0
	global_load_lds_dwordx4 v[154:155], off
	ds_read_b128 v[130:133], v161
	ds_read_b128 v[134:137], v161 offset:1024
	ds_read_b128 v[170:173], v161 offset:2048
	ds_read_b128 v[174:177], v161 offset:3072
	ds_read_b128 v[178:181], v163
	ds_read_b128 v[182:185], v163 offset:1024
	ds_read_b128 v[186:189], v163 offset:2048
	ds_read_b128 v[190:193], v163 offset:3072
	ds_read_b128 v[194:197], v165
	ds_read_b128 v[198:201], v165 offset:1024
	ds_read_b128 v[202:205], v165 offset:2048
	ds_read_b128 v[206:209], v165 offset:3072
	ds_read_b128 v[210:213], v165 offset:4096
	ds_read_b128 v[214:217], v165 offset:5120
	ds_read_b128 v[218:221], v165 offset:6144
	ds_read_b128 v[222:225], v165 offset:7168
	s_waitcnt vmcnt(8)
	s_waitcnt lgkmcnt(0)
	s_barrier
	s_setprio 1
	s_waitcnt lgkmcnt(0)
	v_mfma_f32_16x16x32_bf16 v[126:129], v[130:133], v[194:197], v[126:129]
	v_mfma_f32_16x16x32_bf16 v[122:125], v[170:173], v[194:197], v[122:125]
	v_mfma_f32_16x16x32_bf16 v[118:121], v[130:133], v[202:205], v[118:121]
	v_mfma_f32_16x16x32_bf16 v[110:113], v[170:173], v[202:205], v[110:113]
	v_mfma_f32_16x16x32_bf16 v[102:105], v[130:133], v[210:213], v[102:105]
	v_mfma_f32_16x16x32_bf16 v[94:97], v[170:173], v[210:213], v[94:97]
	v_mfma_f32_16x16x32_bf16 v[86:89], v[130:133], v[218:221], v[86:89]
	v_mfma_f32_16x16x32_bf16 v[78:81], v[170:173], v[218:221], v[78:81]
	v_mfma_f32_16x16x32_bf16 v[126:129], v[134:137], v[198:201], v[126:129]
	v_mfma_f32_16x16x32_bf16 v[122:125], v[174:177], v[198:201], v[122:125]
	v_mfma_f32_16x16x32_bf16 v[118:121], v[134:137], v[206:209], v[118:121]
	v_mfma_f32_16x16x32_bf16 v[110:113], v[174:177], v[206:209], v[110:113]
	v_mfma_f32_16x16x32_bf16 v[102:105], v[134:137], v[214:217], v[102:105]
	v_mfma_f32_16x16x32_bf16 v[94:97], v[174:177], v[214:217], v[94:97]
	v_mfma_f32_16x16x32_bf16 v[86:89], v[134:137], v[222:225], v[86:89]
	v_mfma_f32_16x16x32_bf16 v[78:81], v[174:177], v[222:225], v[78:81]
	s_setprio 0
	s_setprio 1
	v_mfma_f32_16x16x32_bf16 v[114:117], v[178:181], v[194:197], v[114:117]
	v_mfma_f32_16x16x32_bf16 v[106:109], v[186:189], v[194:197], v[106:109]
	v_mfma_f32_16x16x32_bf16 v[98:101], v[178:181], v[202:205], v[98:101]
	v_mfma_f32_16x16x32_bf16 v[90:93], v[186:189], v[202:205], v[90:93]
	v_mfma_f32_16x16x32_bf16 v[82:85], v[178:181], v[210:213], v[82:85]
	v_mfma_f32_16x16x32_bf16 v[74:77], v[186:189], v[210:213], v[74:77]
	v_mfma_f32_16x16x32_bf16 v[70:73], v[178:181], v[218:221], v[70:73]
	v_mfma_f32_16x16x32_bf16 v[66:69], v[186:189], v[218:221], v[66:69]
	v_mfma_f32_16x16x32_bf16 v[114:117], v[182:185], v[198:201], v[114:117]
	v_mfma_f32_16x16x32_bf16 v[106:109], v[190:193], v[198:201], v[106:109]
	v_mfma_f32_16x16x32_bf16 v[98:101], v[182:185], v[206:209], v[98:101]
	v_mfma_f32_16x16x32_bf16 v[90:93], v[190:193], v[206:209], v[90:93]
	v_mfma_f32_16x16x32_bf16 v[82:85], v[182:185], v[214:217], v[82:85]
	v_mfma_f32_16x16x32_bf16 v[74:77], v[190:193], v[214:217], v[74:77]
	v_mfma_f32_16x16x32_bf16 v[70:73], v[182:185], v[222:225], v[70:73]
	v_mfma_f32_16x16x32_bf16 v[66:69], v[190:193], v[222:225], v[66:69]
	s_setprio 0
	s_barrier
	s_add_i32 s75, s67, s55
	v_lshl_add_u64 v[154:155], s[50:51], 0, v[140:141]
	s_mov_b32 m0, s75
	s_nop 0
	global_load_lds_dwordx4 v[154:155], off
	s_add_i32 m0, s75, 0x2000
	s_add_u32 s76, s50, 0x80000
	v_lshl_add_u64 v[166:167], s[50:51], 0, v[144:145]
	s_addc_u32 s77, s51, 0
	s_add_i32 s75, s68, s55
	global_load_lds_dwordx4 v[166:167], off
	v_lshl_add_u64 v[226:227], s[76:77], 0, v[140:141]
	s_mov_b32 m0, s75
	v_lshl_add_u64 v[228:229], s[52:53], 0, v[142:143]
	global_load_lds_dwordx4 v[226:227], off
	v_lshl_add_u64 v[226:227], s[76:77], 0, v[144:145]
	s_add_i32 m0, s75, 0x2000
	s_nop 0
	global_load_lds_dwordx4 v[226:227], off
	v_lshl_add_u64 v[226:227], s[52:53], 0, v[138:139]
	s_mov_b32 m0, s56
	s_nop 0
	global_load_lds_dwordx4 v[226:227], off
	s_mov_b32 m0, s57
	s_nop 0
	global_load_lds_dwordx4 v[228:229], off
	ds_read_b128 v[194:197], v165 offset:16384
	ds_read_b128 v[198:201], v165 offset:17408
	ds_read_b128 v[202:205], v165 offset:18432
	ds_read_b128 v[206:209], v165 offset:19456
	ds_read_b128 v[210:213], v165 offset:20480
	ds_read_b128 v[214:217], v165 offset:21504
	ds_read_b128 v[218:221], v165 offset:22528
	ds_read_b128 v[222:225], v165 offset:23552
	s_waitcnt vmcnt(8)
	s_waitcnt lgkmcnt(0)
	s_barrier
	s_setprio 1
	s_waitcnt lgkmcnt(0)
	v_mfma_f32_16x16x32_bf16 v[62:65], v[130:133], v[194:197], v[62:65]
	v_mfma_f32_16x16x32_bf16 v[58:61], v[170:173], v[194:197], v[58:61]
	v_mfma_f32_16x16x32_bf16 v[54:57], v[130:133], v[202:205], v[54:57]
	v_mfma_f32_16x16x32_bf16 v[46:49], v[170:173], v[202:205], v[46:49]
	v_mfma_f32_16x16x32_bf16 v[38:41], v[130:133], v[210:213], v[38:41]
	v_mfma_f32_16x16x32_bf16 v[30:33], v[170:173], v[210:213], v[30:33]
	v_mfma_f32_16x16x32_bf16 v[22:25], v[130:133], v[218:221], v[22:25]
	v_mfma_f32_16x16x32_bf16 v[14:17], v[170:173], v[218:221], v[14:17]
	v_mfma_f32_16x16x32_bf16 v[62:65], v[134:137], v[198:201], v[62:65]
	v_mfma_f32_16x16x32_bf16 v[58:61], v[174:177], v[198:201], v[58:61]
	v_mfma_f32_16x16x32_bf16 v[54:57], v[134:137], v[206:209], v[54:57]
	v_mfma_f32_16x16x32_bf16 v[46:49], v[174:177], v[206:209], v[46:49]
	v_mfma_f32_16x16x32_bf16 v[38:41], v[134:137], v[214:217], v[38:41]
	v_mfma_f32_16x16x32_bf16 v[30:33], v[174:177], v[214:217], v[30:33]
	v_mfma_f32_16x16x32_bf16 v[22:25], v[134:137], v[222:225], v[22:25]
	v_mfma_f32_16x16x32_bf16 v[14:17], v[174:177], v[222:225], v[14:17]
	s_setprio 0
	s_setprio 1
	v_mfma_f32_16x16x32_bf16 v[50:53], v[178:181], v[194:197], v[50:53]
	v_mfma_f32_16x16x32_bf16 v[42:45], v[186:189], v[194:197], v[42:45]
	v_mfma_f32_16x16x32_bf16 v[34:37], v[178:181], v[202:205], v[34:37]
	v_mfma_f32_16x16x32_bf16 v[26:29], v[186:189], v[202:205], v[26:29]
	v_mfma_f32_16x16x32_bf16 v[18:21], v[178:181], v[210:213], v[18:21]
	v_mfma_f32_16x16x32_bf16 v[10:13], v[186:189], v[210:213], v[10:13]
	v_mfma_f32_16x16x32_bf16 v[6:9], v[178:181], v[218:221], v[6:9]
	v_mfma_f32_16x16x32_bf16 v[2:5], v[186:189], v[218:221], v[2:5]
	v_mfma_f32_16x16x32_bf16 v[50:53], v[182:185], v[198:201], v[50:53]
	v_mfma_f32_16x16x32_bf16 v[42:45], v[190:193], v[198:201], v[42:45]
	v_mfma_f32_16x16x32_bf16 v[34:37], v[182:185], v[206:209], v[34:37]
	v_mfma_f32_16x16x32_bf16 v[26:29], v[190:193], v[206:209], v[26:29]
	v_mfma_f32_16x16x32_bf16 v[18:21], v[182:185], v[214:217], v[18:21]
	v_mfma_f32_16x16x32_bf16 v[10:13], v[190:193], v[214:217], v[10:13]
	v_mfma_f32_16x16x32_bf16 v[6:9], v[182:185], v[222:225], v[6:9]
	v_mfma_f32_16x16x32_bf16 v[2:5], v[190:193], v[222:225], v[2:5]
	s_setprio 0
	s_barrier
	s_add_i32 s75, 0, 0x18000
	s_add_i32 s76, 0, 0x1c000
	s_add_u32 s52, s52, 0x80000
	s_addc_u32 s53, s53, 0
	s_mov_b32 m0, s58
	v_lshl_add_u64 v[230:231], s[52:53], 0, v[138:139]
	global_load_lds_dwordx4 v[230:231], off
	v_lshl_add_u64 v[230:231], s[52:53], 0, v[142:143]
	s_mov_b32 m0, s59
	s_nop 0
	global_load_lds_dwordx4 v[230:231], off
	v_add_u32_e32 v156, s75, v159
	ds_read_b128 v[130:133], v156
	ds_read_b128 v[134:137], v156 offset:1024
	ds_read_b128 v[170:173], v156 offset:2048
	ds_read_b128 v[174:177], v156 offset:3072
	v_add_u32_e32 v156, s76, v159
	ds_read_b128 v[178:181], v156
	ds_read_b128 v[182:185], v156 offset:1024
	ds_read_b128 v[186:189], v156 offset:2048
	ds_read_b128 v[190:193], v156 offset:3072
	ds_read_b128 v[194:197], v165 offset:32768
	ds_read_b128 v[198:201], v165 offset:33792
	ds_read_b128 v[202:205], v165 offset:34816
	ds_read_b128 v[206:209], v165 offset:35840
	ds_read_b128 v[210:213], v165 offset:36864
	ds_read_b128 v[214:217], v165 offset:37888
	ds_read_b128 v[218:221], v165 offset:38912
	ds_read_b128 v[222:225], v165 offset:39936
	s_waitcnt vmcnt(8)
	s_waitcnt lgkmcnt(0)
	s_barrier
	s_setprio 1
	s_waitcnt lgkmcnt(0)
	v_mfma_f32_16x16x32_bf16 v[126:129], v[130:133], v[194:197], v[126:129]
	v_mfma_f32_16x16x32_bf16 v[122:125], v[170:173], v[194:197], v[122:125]
	v_mfma_f32_16x16x32_bf16 v[118:121], v[130:133], v[202:205], v[118:121]
	v_mfma_f32_16x16x32_bf16 v[110:113], v[170:173], v[202:205], v[110:113]
	v_mfma_f32_16x16x32_bf16 v[102:105], v[130:133], v[210:213], v[102:105]
	v_mfma_f32_16x16x32_bf16 v[94:97], v[170:173], v[210:213], v[94:97]
	v_mfma_f32_16x16x32_bf16 v[86:89], v[130:133], v[218:221], v[86:89]
	v_mfma_f32_16x16x32_bf16 v[78:81], v[170:173], v[218:221], v[78:81]
	v_mfma_f32_16x16x32_bf16 v[126:129], v[134:137], v[198:201], v[126:129]
	v_mfma_f32_16x16x32_bf16 v[122:125], v[174:177], v[198:201], v[122:125]
	v_mfma_f32_16x16x32_bf16 v[118:121], v[134:137], v[206:209], v[118:121]
	v_mfma_f32_16x16x32_bf16 v[110:113], v[174:177], v[206:209], v[110:113]
	v_mfma_f32_16x16x32_bf16 v[102:105], v[134:137], v[214:217], v[102:105]
	v_mfma_f32_16x16x32_bf16 v[94:97], v[174:177], v[214:217], v[94:97]
	v_mfma_f32_16x16x32_bf16 v[86:89], v[134:137], v[222:225], v[86:89]
	v_mfma_f32_16x16x32_bf16 v[78:81], v[174:177], v[222:225], v[78:81]
	s_setprio 0
	s_setprio 1
	v_mfma_f32_16x16x32_bf16 v[114:117], v[178:181], v[194:197], v[114:117]
	v_mfma_f32_16x16x32_bf16 v[106:109], v[186:189], v[194:197], v[106:109]
	v_mfma_f32_16x16x32_bf16 v[98:101], v[178:181], v[202:205], v[98:101]
	v_mfma_f32_16x16x32_bf16 v[90:93], v[186:189], v[202:205], v[90:93]
	v_mfma_f32_16x16x32_bf16 v[82:85], v[178:181], v[210:213], v[82:85]
	v_mfma_f32_16x16x32_bf16 v[74:77], v[186:189], v[210:213], v[74:77]
	v_mfma_f32_16x16x32_bf16 v[70:73], v[178:181], v[218:221], v[70:73]
	v_mfma_f32_16x16x32_bf16 v[66:69], v[186:189], v[218:221], v[66:69]
	v_mfma_f32_16x16x32_bf16 v[114:117], v[182:185], v[198:201], v[114:117]
	v_mfma_f32_16x16x32_bf16 v[106:109], v[190:193], v[198:201], v[106:109]
	v_mfma_f32_16x16x32_bf16 v[98:101], v[182:185], v[206:209], v[98:101]
	v_mfma_f32_16x16x32_bf16 v[90:93], v[190:193], v[206:209], v[90:93]
	v_mfma_f32_16x16x32_bf16 v[82:85], v[182:185], v[214:217], v[82:85]
	v_mfma_f32_16x16x32_bf16 v[74:77], v[190:193], v[214:217], v[74:77]
	v_mfma_f32_16x16x32_bf16 v[70:73], v[182:185], v[222:225], v[70:73]
	v_mfma_f32_16x16x32_bf16 v[66:69], v[190:193], v[222:225], v[66:69]
	s_setprio 0
	s_barrier
	s_add_i32 s52, s75, s55
	v_lshl_add_u64 v[154:155], v[154:155], 0, s[12:13]
	s_mov_b32 m0, s52
	s_nop 0
	global_load_lds_dwordx4 v[154:155], off
	s_add_i32 m0, s52, 0x2000
	s_add_u32 s50, s50, 0x80080
	v_lshl_add_u64 v[154:155], v[166:167], 0, s[12:13]
	s_addc_u32 s51, s51, 0
	s_add_i32 s52, s76, s55
	global_load_lds_dwordx4 v[154:155], off
	v_lshl_add_u64 v[154:155], s[50:51], 0, v[140:141]
	s_mov_b32 m0, s52
	s_nop 0
	global_load_lds_dwordx4 v[154:155], off
	v_lshl_add_u64 v[154:155], s[50:51], 0, v[144:145]
	s_add_i32 m0, s52, 0x2000
	s_nop 0
	global_load_lds_dwordx4 v[154:155], off
	v_lshl_add_u64 v[154:155], v[226:227], 0, s[12:13]
	s_mov_b32 m0, s64
	s_nop 0
	global_load_lds_dwordx4 v[154:155], off
	v_lshl_add_u64 v[154:155], v[228:229], 0, s[12:13]
	s_mov_b32 m0, s65
	s_nop 0
	global_load_lds_dwordx4 v[154:155], off
	ds_read_b128 v[194:197], v165 offset:49152
	ds_read_b128 v[198:201], v165 offset:50176
	ds_read_b128 v[202:205], v165 offset:51200
	ds_read_b128 v[206:209], v165 offset:52224
	ds_read_b128 v[210:213], v165 offset:53248
	ds_read_b128 v[214:217], v165 offset:54272
	ds_read_b128 v[218:221], v165 offset:55296
	ds_read_b128 v[222:225], v165 offset:56320
	s_waitcnt vmcnt(8)
	s_waitcnt lgkmcnt(0)
	s_barrier
	s_setprio 1
	s_waitcnt lgkmcnt(0)
	v_mfma_f32_16x16x32_bf16 v[62:65], v[130:133], v[194:197], v[62:65]
	v_mfma_f32_16x16x32_bf16 v[58:61], v[170:173], v[194:197], v[58:61]
	v_mfma_f32_16x16x32_bf16 v[54:57], v[130:133], v[202:205], v[54:57]
	v_mfma_f32_16x16x32_bf16 v[46:49], v[170:173], v[202:205], v[46:49]
	v_mfma_f32_16x16x32_bf16 v[38:41], v[130:133], v[210:213], v[38:41]
	v_mfma_f32_16x16x32_bf16 v[30:33], v[170:173], v[210:213], v[30:33]
	v_mfma_f32_16x16x32_bf16 v[22:25], v[130:133], v[218:221], v[22:25]
	v_mfma_f32_16x16x32_bf16 v[14:17], v[170:173], v[218:221], v[14:17]
	v_mfma_f32_16x16x32_bf16 v[62:65], v[134:137], v[198:201], v[62:65]
	v_mfma_f32_16x16x32_bf16 v[58:61], v[174:177], v[198:201], v[58:61]
	v_mfma_f32_16x16x32_bf16 v[54:57], v[134:137], v[206:209], v[54:57]
	v_mfma_f32_16x16x32_bf16 v[46:49], v[174:177], v[206:209], v[46:49]
	v_mfma_f32_16x16x32_bf16 v[38:41], v[134:137], v[214:217], v[38:41]
	v_mfma_f32_16x16x32_bf16 v[30:33], v[174:177], v[214:217], v[30:33]
	v_mfma_f32_16x16x32_bf16 v[22:25], v[134:137], v[222:225], v[22:25]
	v_mfma_f32_16x16x32_bf16 v[14:17], v[174:177], v[222:225], v[14:17]
	s_setprio 0
	s_setprio 1
	v_mfma_f32_16x16x32_bf16 v[50:53], v[178:181], v[194:197], v[50:53]
	v_mfma_f32_16x16x32_bf16 v[42:45], v[186:189], v[194:197], v[42:45]
	v_mfma_f32_16x16x32_bf16 v[34:37], v[178:181], v[202:205], v[34:37]
	v_mfma_f32_16x16x32_bf16 v[26:29], v[186:189], v[202:205], v[26:29]
	v_mfma_f32_16x16x32_bf16 v[18:21], v[178:181], v[210:213], v[18:21]
	v_mfma_f32_16x16x32_bf16 v[10:13], v[186:189], v[210:213], v[10:13]
	v_mfma_f32_16x16x32_bf16 v[6:9], v[178:181], v[218:221], v[6:9]
	v_mfma_f32_16x16x32_bf16 v[2:5], v[186:189], v[218:221], v[2:5]
	v_mfma_f32_16x16x32_bf16 v[50:53], v[182:185], v[198:201], v[50:53]
	v_mfma_f32_16x16x32_bf16 v[42:45], v[190:193], v[198:201], v[42:45]
	v_mfma_f32_16x16x32_bf16 v[34:37], v[182:185], v[206:209], v[34:37]
	v_mfma_f32_16x16x32_bf16 v[26:29], v[190:193], v[206:209], v[26:29]
	v_mfma_f32_16x16x32_bf16 v[18:21], v[182:185], v[214:217], v[18:21]
	v_mfma_f32_16x16x32_bf16 v[10:13], v[190:193], v[214:217], v[10:13]
	v_mfma_f32_16x16x32_bf16 v[6:9], v[182:185], v[222:225], v[6:9]
	v_mfma_f32_16x16x32_bf16 v[2:5], v[190:193], v[222:225], v[2:5]
	s_setprio 0
	s_barrier
	s_add_i32 s74, s74, 2
	s_add_u32 s48, s48, 0x100
	s_addc_u32 s49, s49, 0
	s_add_u32 s72, s72, 0x100
	s_addc_u32 s73, s73, 0
	s_cmp_gt_u32 s74, 29
	s_cbranch_scc0 .LBB0_117
	s_and_b64 vcc, exec, s[28:29]
	s_cbranch_vccz .LBB0_120
	s_barrier

.LBB0_1855:
	s_add_u32 s26, s24, 0x100
	s_addc_u32 s27, s25, 0
	s_cmp_eq_u32 s55, 60
	s_cselect_b32 s31, s19, s27
	s_cselect_b32 s30, s51, s26
	s_cselect_b32 s29, s17, s54
	s_cselect_b32 s28, s52, s53
	v_lshl_add_u64 v[212:213], s[24:25], 0, v[134:135]
	s_add_i32 m0, s5, 0xc000
	s_nop 0
	global_load_lds_dwordx4 v[212:213], off
	v_lshl_add_u64 v[212:213], s[24:25], 0, v[136:137]
	s_add_i32 m0, s5, 0xe000
	s_nop 0
	global_load_lds_dwordx4 v[212:213], off
	ds_read_b128 v[142:145], v148
	ds_read_b128 v[152:155], v148 offset:1024
	ds_read_b128 v[156:159], v148 offset:2048
	ds_read_b128 v[160:163], v148 offset:3072
	ds_read_b128 v[164:167], v149
	ds_read_b128 v[168:171], v149 offset:1024
	ds_read_b128 v[172:175], v149 offset:2048
	ds_read_b128 v[176:179], v149 offset:3072
	ds_read_b128 v[180:183], v150
	ds_read_b128 v[184:187], v150 offset:1024
	ds_read_b128 v[188:191], v150 offset:2048
	ds_read_b128 v[192:195], v150 offset:3072
	ds_read_b128 v[196:199], v150 offset:4096
	ds_read_b128 v[200:203], v150 offset:5120
	ds_read_b128 v[204:207], v150 offset:6144
	ds_read_b128 v[208:211], v150 offset:7168
	s_waitcnt vmcnt(8)
	s_waitcnt lgkmcnt(0)
	s_barrier
	s_setprio 1
	s_waitcnt lgkmcnt(0)
	v_mfma_f32_16x16x32_bf16 v[126:129], v[142:145], v[180:183], v[126:129]
	v_mfma_f32_16x16x32_bf16 v[122:125], v[156:159], v[180:183], v[122:125]
	v_mfma_f32_16x16x32_bf16 v[110:113], v[142:145], v[188:191], v[110:113]
	v_mfma_f32_16x16x32_bf16 v[106:109], v[156:159], v[188:191], v[106:109]
	v_mfma_f32_16x16x32_bf16 v[94:97], v[142:145], v[196:199], v[94:97]
	v_mfma_f32_16x16x32_bf16 v[90:93], v[156:159], v[196:199], v[90:93]
	v_mfma_f32_16x16x32_bf16 v[78:81], v[142:145], v[204:207], v[78:81]
	v_mfma_f32_16x16x32_bf16 v[74:77], v[156:159], v[204:207], v[74:77]
	v_mfma_f32_16x16x32_bf16 v[126:129], v[152:155], v[184:187], v[126:129]
	v_mfma_f32_16x16x32_bf16 v[122:125], v[160:163], v[184:187], v[122:125]
	v_mfma_f32_16x16x32_bf16 v[110:113], v[152:155], v[192:195], v[110:113]
	v_mfma_f32_16x16x32_bf16 v[106:109], v[160:163], v[192:195], v[106:109]
	v_mfma_f32_16x16x32_bf16 v[94:97], v[152:155], v[200:203], v[94:97]
	v_mfma_f32_16x16x32_bf16 v[90:93], v[160:163], v[200:203], v[90:93]
	v_mfma_f32_16x16x32_bf16 v[78:81], v[152:155], v[208:211], v[78:81]
	v_mfma_f32_16x16x32_bf16 v[74:77], v[160:163], v[208:211], v[74:77]
	s_setprio 0
	s_setprio 1
	v_mfma_f32_16x16x32_bf16 v[118:121], v[164:167], v[180:183], v[118:121]
	v_mfma_f32_16x16x32_bf16 v[114:117], v[172:175], v[180:183], v[114:117]
	v_mfma_f32_16x16x32_bf16 v[102:105], v[164:167], v[188:191], v[102:105]
	v_mfma_f32_16x16x32_bf16 v[98:101], v[172:175], v[188:191], v[98:101]
	v_mfma_f32_16x16x32_bf16 v[86:89], v[164:167], v[196:199], v[86:89]
	v_mfma_f32_16x16x32_bf16 v[82:85], v[172:175], v[196:199], v[82:85]
	v_mfma_f32_16x16x32_bf16 v[70:73], v[164:167], v[204:207], v[70:73]
	v_mfma_f32_16x16x32_bf16 v[66:69], v[172:175], v[204:207], v[66:69]
	v_mfma_f32_16x16x32_bf16 v[118:121], v[168:171], v[184:187], v[118:121]
	v_mfma_f32_16x16x32_bf16 v[114:117], v[176:179], v[184:187], v[114:117]
	v_mfma_f32_16x16x32_bf16 v[102:105], v[168:171], v[192:195], v[102:105]
	v_mfma_f32_16x16x32_bf16 v[98:101], v[176:179], v[192:195], v[98:101]
	v_mfma_f32_16x16x32_bf16 v[86:89], v[168:171], v[200:203], v[86:89]
	v_mfma_f32_16x16x32_bf16 v[82:85], v[176:179], v[200:203], v[82:85]
	v_mfma_f32_16x16x32_bf16 v[70:73], v[168:171], v[208:211], v[70:73]
	v_mfma_f32_16x16x32_bf16 v[66:69], v[176:179], v[208:211], v[66:69]
	s_setprio 0
	s_barrier
	s_add_i32 s24, s48, s37
	v_lshl_add_u64 v[212:213], s[28:29], 0, v[130:131]
	s_mov_b32 m0, s24
	s_nop 0
	global_load_lds_dwordx4 v[212:213], off
	s_add_i32 m0, s24, 0x2000
	s_add_u32 s24, s28, 0x100000
	v_lshl_add_u64 v[214:215], s[28:29], 0, v[132:133]
	s_addc_u32 s25, s29, 0
	s_add_i32 s56, s49, s37
	global_load_lds_dwordx4 v[214:215], off
	v_lshl_add_u64 v[216:217], s[24:25], 0, v[130:131]
	s_mov_b32 m0, s56
	v_lshl_add_u64 v[218:219], s[30:31], 0, v[132:133]
	global_load_lds_dwordx4 v[216:217], off
	v_lshl_add_u64 v[216:217], s[24:25], 0, v[132:133]
	s_add_i32 m0, s56, 0x2000
	s_nop 0
	global_load_lds_dwordx4 v[216:217], off
	v_lshl_add_u64 v[216:217], s[30:31], 0, v[130:131]
	s_mov_b32 m0, s5
	s_nop 0
	global_load_lds_dwordx4 v[216:217], off
	s_mov_b32 m0, s38
	s_nop 0
	global_load_lds_dwordx4 v[218:219], off
	ds_read_b128 v[180:183], v150 offset:16384
	ds_read_b128 v[184:187], v150 offset:17408
	ds_read_b128 v[188:191], v150 offset:18432
	ds_read_b128 v[192:195], v150 offset:19456
	ds_read_b128 v[196:199], v150 offset:20480
	ds_read_b128 v[200:203], v150 offset:21504
	ds_read_b128 v[204:207], v150 offset:22528
	ds_read_b128 v[208:211], v150 offset:23552
	s_waitcnt vmcnt(8)
	s_waitcnt lgkmcnt(0)
	s_barrier
	s_setprio 1
	s_waitcnt lgkmcnt(0)
	v_mfma_f32_16x16x32_bf16 v[62:65], v[142:145], v[180:183], v[62:65]
	v_mfma_f32_16x16x32_bf16 v[58:61], v[156:159], v[180:183], v[58:61]
	v_mfma_f32_16x16x32_bf16 v[46:49], v[142:145], v[188:191], v[46:49]
	v_mfma_f32_16x16x32_bf16 v[42:45], v[156:159], v[188:191], v[42:45]
	v_mfma_f32_16x16x32_bf16 v[30:33], v[142:145], v[196:199], v[30:33]
	v_mfma_f32_16x16x32_bf16 v[26:29], v[156:159], v[196:199], v[26:29]
	v_mfma_f32_16x16x32_bf16 v[14:17], v[142:145], v[204:207], v[14:17]
	v_mfma_f32_16x16x32_bf16 v[10:13], v[156:159], v[204:207], v[10:13]
	v_mfma_f32_16x16x32_bf16 v[62:65], v[152:155], v[184:187], v[62:65]
	v_mfma_f32_16x16x32_bf16 v[58:61], v[160:163], v[184:187], v[58:61]
	v_mfma_f32_16x16x32_bf16 v[46:49], v[152:155], v[192:195], v[46:49]
	v_mfma_f32_16x16x32_bf16 v[42:45], v[160:163], v[192:195], v[42:45]
	v_mfma_f32_16x16x32_bf16 v[30:33], v[152:155], v[200:203], v[30:33]
	v_mfma_f32_16x16x32_bf16 v[26:29], v[160:163], v[200:203], v[26:29]
	v_mfma_f32_16x16x32_bf16 v[14:17], v[152:155], v[208:211], v[14:17]
	v_mfma_f32_16x16x32_bf16 v[10:13], v[160:163], v[208:211], v[10:13]
	s_setprio 0
	s_setprio 1
	v_mfma_f32_16x16x32_bf16 v[54:57], v[164:167], v[180:183], v[54:57]
	v_mfma_f32_16x16x32_bf16 v[50:53], v[172:175], v[180:183], v[50:53]
	v_mfma_f32_16x16x32_bf16 v[38:41], v[164:167], v[188:191], v[38:41]
	v_mfma_f32_16x16x32_bf16 v[34:37], v[172:175], v[188:191], v[34:37]
	v_mfma_f32_16x16x32_bf16 v[22:25], v[164:167], v[196:199], v[22:25]
	v_mfma_f32_16x16x32_bf16 v[18:21], v[172:175], v[196:199], v[18:21]
	v_mfma_f32_16x16x32_bf16 v[6:9], v[164:167], v[204:207], v[6:9]
	v_mfma_f32_16x16x32_bf16 v[2:5], v[172:175], v[204:207], v[2:5]
	v_mfma_f32_16x16x32_bf16 v[54:57], v[168:171], v[184:187], v[54:57]
	v_mfma_f32_16x16x32_bf16 v[50:53], v[176:179], v[184:187], v[50:53]
	v_mfma_f32_16x16x32_bf16 v[38:41], v[168:171], v[192:195], v[38:41]
	v_mfma_f32_16x16x32_bf16 v[34:37], v[176:179], v[192:195], v[34:37]
	v_mfma_f32_16x16x32_bf16 v[22:25], v[168:171], v[200:203], v[22:25]
	v_mfma_f32_16x16x32_bf16 v[18:21], v[176:179], v[200:203], v[18:21]
	v_mfma_f32_16x16x32_bf16 v[6:9], v[168:171], v[208:211], v[6:9]
	v_mfma_f32_16x16x32_bf16 v[2:5], v[176:179], v[208:211], v[2:5]
	s_setprio 0
	s_barrier
	s_add_i32 s56, 0, 0x18000
	s_add_i32 s57, 0, 0x1c000
	s_add_u32 s24, s30, 0x100000
	s_addc_u32 s25, s31, 0
	s_mov_b32 m0, s39
	v_lshl_add_u64 v[220:221], s[24:25], 0, v[130:131]
	global_load_lds_dwordx4 v[220:221], off
	v_lshl_add_u64 v[220:221], s[24:25], 0, v[132:133]
	s_mov_b32 m0, s40
	s_nop 0
	global_load_lds_dwordx4 v[220:221], off
	v_add_u32_e32 v160, s56, v147
	v_add_u32_e32 v176, s57, v147
	ds_read_b128 v[142:145], v160
	ds_read_b128 v[152:155], v160 offset:1024
	ds_read_b128 v[156:159], v160 offset:2048
	ds_read_b128 v[160:163], v160 offset:3072
	ds_read_b128 v[164:167], v176
	ds_read_b128 v[168:171], v176 offset:1024
	ds_read_b128 v[172:175], v176 offset:2048
	ds_read_b128 v[176:179], v176 offset:3072
	ds_read_b128 v[180:183], v150 offset:32768
	ds_read_b128 v[184:187], v150 offset:33792
	ds_read_b128 v[188:191], v150 offset:34816
	ds_read_b128 v[192:195], v150 offset:35840
	ds_read_b128 v[196:199], v150 offset:36864
	ds_read_b128 v[200:203], v150 offset:37888
	ds_read_b128 v[204:207], v150 offset:38912
	ds_read_b128 v[208:211], v150 offset:39936
	s_waitcnt vmcnt(8)
	s_waitcnt lgkmcnt(0)
	s_barrier
	s_setprio 1
	s_waitcnt lgkmcnt(0)
	v_mfma_f32_16x16x32_bf16 v[126:129], v[142:145], v[180:183], v[126:129]
	v_mfma_f32_16x16x32_bf16 v[122:125], v[156:159], v[180:183], v[122:125]
	v_mfma_f32_16x16x32_bf16 v[110:113], v[142:145], v[188:191], v[110:113]
	v_mfma_f32_16x16x32_bf16 v[106:109], v[156:159], v[188:191], v[106:109]
	v_mfma_f32_16x16x32_bf16 v[94:97], v[142:145], v[196:199], v[94:97]
	v_mfma_f32_16x16x32_bf16 v[90:93], v[156:159], v[196:199], v[90:93]
	v_mfma_f32_16x16x32_bf16 v[78:81], v[142:145], v[204:207], v[78:81]
	v_mfma_f32_16x16x32_bf16 v[74:77], v[156:159], v[204:207], v[74:77]
	v_mfma_f32_16x16x32_bf16 v[126:129], v[152:155], v[184:187], v[126:129]
	v_mfma_f32_16x16x32_bf16 v[122:125], v[160:163], v[184:187], v[122:125]
	v_mfma_f32_16x16x32_bf16 v[110:113], v[152:155], v[192:195], v[110:113]
	v_mfma_f32_16x16x32_bf16 v[106:109], v[160:163], v[192:195], v[106:109]
	v_mfma_f32_16x16x32_bf16 v[94:97], v[152:155], v[200:203], v[94:97]
	v_mfma_f32_16x16x32_bf16 v[90:93], v[160:163], v[200:203], v[90:93]
	v_mfma_f32_16x16x32_bf16 v[78:81], v[152:155], v[208:211], v[78:81]
	v_mfma_f32_16x16x32_bf16 v[74:77], v[160:163], v[208:211], v[74:77]
	s_setprio 0
	s_setprio 1
	v_mfma_f32_16x16x32_bf16 v[118:121], v[164:167], v[180:183], v[118:121]
	v_mfma_f32_16x16x32_bf16 v[114:117], v[172:175], v[180:183], v[114:117]
	v_mfma_f32_16x16x32_bf16 v[102:105], v[164:167], v[188:191], v[102:105]
	v_mfma_f32_16x16x32_bf16 v[98:101], v[172:175], v[188:191], v[98:101]
	v_mfma_f32_16x16x32_bf16 v[86:89], v[164:167], v[196:199], v[86:89]
	v_mfma_f32_16x16x32_bf16 v[82:85], v[172:175], v[196:199], v[82:85]
	v_mfma_f32_16x16x32_bf16 v[70:73], v[164:167], v[204:207], v[70:73]
	v_mfma_f32_16x16x32_bf16 v[66:69], v[172:175], v[204:207], v[66:69]
	v_mfma_f32_16x16x32_bf16 v[118:121], v[168:171], v[184:187], v[118:121]
	v_mfma_f32_16x16x32_bf16 v[114:117], v[176:179], v[184:187], v[114:117]
	v_mfma_f32_16x16x32_bf16 v[102:105], v[168:171], v[192:195], v[102:105]
	v_mfma_f32_16x16x32_bf16 v[98:101], v[176:179], v[192:195], v[98:101]
	v_mfma_f32_16x16x32_bf16 v[86:89], v[168:171], v[200:203], v[86:89]
	v_mfma_f32_16x16x32_bf16 v[82:85], v[176:179], v[200:203], v[82:85]
	v_mfma_f32_16x16x32_bf16 v[70:73], v[168:171], v[208:211], v[70:73]
	v_mfma_f32_16x16x32_bf16 v[66:69], v[176:179], v[208:211], v[66:69]
	s_setprio 0
	s_barrier
	s_add_i32 s24, s56, s37
	v_lshl_add_u64 v[212:213], v[212:213], 0, s[12:13]
	s_mov_b32 m0, s24
	s_nop 0
	global_load_lds_dwordx4 v[212:213], off
	s_add_i32 m0, s24, 0x2000
	s_add_u32 s24, s28, 0x100080
	v_lshl_add_u64 v[212:213], v[214:215], 0, s[12:13]
	s_addc_u32 s25, s29, 0
	s_add_i32 s28, s57, s37
	global_load_lds_dwordx4 v[212:213], off
	v_lshl_add_u64 v[212:213], s[24:25], 0, v[130:131]
	s_mov_b32 m0, s28
	s_nop 0
	global_load_lds_dwordx4 v[212:213], off
	v_lshl_add_u64 v[212:213], s[24:25], 0, v[132:133]
	s_add_i32 m0, s28, 0x2000
	s_nop 0
	global_load_lds_dwordx4 v[212:213], off
	v_lshl_add_u64 v[212:213], v[216:217], 0, s[12:13]
	s_mov_b32 m0, s44
	s_nop 0
	global_load_lds_dwordx4 v[212:213], off
	v_lshl_add_u64 v[212:213], v[218:219], 0, s[12:13]
	s_mov_b32 m0, s45
	s_nop 0
	global_load_lds_dwordx4 v[212:213], off
	ds_read_b128 v[180:183], v150 offset:49152
	ds_read_b128 v[184:187], v150 offset:50176
	ds_read_b128 v[188:191], v150 offset:51200
	ds_read_b128 v[192:195], v150 offset:52224
	ds_read_b128 v[196:199], v150 offset:53248
	ds_read_b128 v[200:203], v150 offset:54272
	ds_read_b128 v[204:207], v150 offset:55296
	ds_read_b128 v[208:211], v150 offset:56320
	s_waitcnt vmcnt(8)
	s_waitcnt lgkmcnt(0)
	s_barrier
	s_setprio 1
	s_waitcnt lgkmcnt(0)
	v_mfma_f32_16x16x32_bf16 v[62:65], v[142:145], v[180:183], v[62:65]
	v_mfma_f32_16x16x32_bf16 v[58:61], v[156:159], v[180:183], v[58:61]
	v_mfma_f32_16x16x32_bf16 v[46:49], v[142:145], v[188:191], v[46:49]
	v_mfma_f32_16x16x32_bf16 v[42:45], v[156:159], v[188:191], v[42:45]
	v_mfma_f32_16x16x32_bf16 v[30:33], v[142:145], v[196:199], v[30:33]
	v_mfma_f32_16x16x32_bf16 v[26:29], v[156:159], v[196:199], v[26:29]
	v_mfma_f32_16x16x32_bf16 v[14:17], v[142:145], v[204:207], v[14:17]
	v_mfma_f32_16x16x32_bf16 v[10:13], v[156:159], v[204:207], v[10:13]
	v_mfma_f32_16x16x32_bf16 v[62:65], v[152:155], v[184:187], v[62:65]
	v_mfma_f32_16x16x32_bf16 v[58:61], v[160:163], v[184:187], v[58:61]
	v_mfma_f32_16x16x32_bf16 v[46:49], v[152:155], v[192:195], v[46:49]
	v_mfma_f32_16x16x32_bf16 v[42:45], v[160:163], v[192:195], v[42:45]
	v_mfma_f32_16x16x32_bf16 v[30:33], v[152:155], v[200:203], v[30:33]
	v_mfma_f32_16x16x32_bf16 v[26:29], v[160:163], v[200:203], v[26:29]
	v_mfma_f32_16x16x32_bf16 v[14:17], v[152:155], v[208:211], v[14:17]
	v_mfma_f32_16x16x32_bf16 v[10:13], v[160:163], v[208:211], v[10:13]
	s_setprio 0
	s_setprio 1
	v_mfma_f32_16x16x32_bf16 v[54:57], v[164:167], v[180:183], v[54:57]
	v_mfma_f32_16x16x32_bf16 v[50:53], v[172:175], v[180:183], v[50:53]
	v_mfma_f32_16x16x32_bf16 v[38:41], v[164:167], v[188:191], v[38:41]
	v_mfma_f32_16x16x32_bf16 v[34:37], v[172:175], v[188:191], v[34:37]
	v_mfma_f32_16x16x32_bf16 v[22:25], v[164:167], v[196:199], v[22:25]
	v_mfma_f32_16x16x32_bf16 v[18:21], v[172:175], v[196:199], v[18:21]
	v_mfma_f32_16x16x32_bf16 v[6:9], v[164:167], v[204:207], v[6:9]
	v_mfma_f32_16x16x32_bf16 v[2:5], v[172:175], v[204:207], v[2:5]
	v_mfma_f32_16x16x32_bf16 v[54:57], v[168:171], v[184:187], v[54:57]
	v_mfma_f32_16x16x32_bf16 v[50:53], v[176:179], v[184:187], v[50:53]
	v_mfma_f32_16x16x32_bf16 v[38:41], v[168:171], v[192:195], v[38:41]
	v_mfma_f32_16x16x32_bf16 v[34:37], v[176:179], v[192:195], v[34:37]
	v_mfma_f32_16x16x32_bf16 v[22:25], v[168:171], v[200:203], v[22:25]
	v_mfma_f32_16x16x32_bf16 v[18:21], v[176:179], v[200:203], v[18:21]
	v_mfma_f32_16x16x32_bf16 v[6:9], v[168:171], v[208:211], v[6:9]
	v_mfma_f32_16x16x32_bf16 v[2:5], v[176:179], v[208:211], v[2:5]
	s_setprio 0
	s_barrier
	s_add_i32 s55, s55, 2
	s_add_u32 s53, s53, 0x100
	s_addc_u32 s54, s54, 0
	s_cmp_gt_u32 s55, 61
	s_mov_b64 s[24:25], s[26:27]
	s_cbranch_scc0 .LBB0_1855
	s_and_b64 vcc, exec, s[14:15]
	s_cbranch_vccz .LBB0_1858
	s_barrier

.LBB0_2118:
	s_add_u32 s20, s18, 0x100
	s_addc_u32 s21, s19, 0
	s_cmpk_eq_i32 s49, 0x54
	s_cselect_b32 s25, s7, s21
	s_cselect_b32 s24, s6, s20
	s_cselect_b32 s23, s17, s48
	s_cselect_b32 s22, s16, s47
	v_lshl_add_u64 v[212:213], s[18:19], 0, v[134:135]
	s_add_i32 m0, s30, 0xc000
	s_nop 0
	global_load_lds_dwordx4 v[212:213], off
	v_lshl_add_u64 v[212:213], s[18:19], 0, v[136:137]
	s_add_i32 m0, s30, 0xe000
	s_nop 0
	global_load_lds_dwordx4 v[212:213], off
	ds_read_b128 v[142:145], v148
	ds_read_b128 v[152:155], v148 offset:1024
	ds_read_b128 v[156:159], v148 offset:2048
	ds_read_b128 v[160:163], v148 offset:3072
	ds_read_b128 v[164:167], v149
	ds_read_b128 v[168:171], v149 offset:1024
	ds_read_b128 v[172:175], v149 offset:2048
	ds_read_b128 v[176:179], v149 offset:3072
	ds_read_b128 v[180:183], v150
	ds_read_b128 v[184:187], v150 offset:1024
	ds_read_b128 v[188:191], v150 offset:2048
	ds_read_b128 v[192:195], v150 offset:3072
	ds_read_b128 v[196:199], v150 offset:4096
	ds_read_b128 v[200:203], v150 offset:5120
	ds_read_b128 v[204:207], v150 offset:6144
	ds_read_b128 v[208:211], v150 offset:7168
	s_waitcnt vmcnt(8)
	s_waitcnt lgkmcnt(0)
	s_barrier
	s_setprio 1
	s_waitcnt lgkmcnt(0)
	v_mfma_f32_16x16x32_bf16 v[126:129], v[142:145], v[180:183], v[126:129]
	v_mfma_f32_16x16x32_bf16 v[122:125], v[156:159], v[180:183], v[122:125]
	v_mfma_f32_16x16x32_bf16 v[110:113], v[142:145], v[188:191], v[110:113]
	v_mfma_f32_16x16x32_bf16 v[106:109], v[156:159], v[188:191], v[106:109]
	v_mfma_f32_16x16x32_bf16 v[94:97], v[142:145], v[196:199], v[94:97]
	v_mfma_f32_16x16x32_bf16 v[90:93], v[156:159], v[196:199], v[90:93]
	v_mfma_f32_16x16x32_bf16 v[78:81], v[142:145], v[204:207], v[78:81]
	v_mfma_f32_16x16x32_bf16 v[74:77], v[156:159], v[204:207], v[74:77]
	v_mfma_f32_16x16x32_bf16 v[126:129], v[152:155], v[184:187], v[126:129]
	v_mfma_f32_16x16x32_bf16 v[122:125], v[160:163], v[184:187], v[122:125]
	v_mfma_f32_16x16x32_bf16 v[110:113], v[152:155], v[192:195], v[110:113]
	v_mfma_f32_16x16x32_bf16 v[106:109], v[160:163], v[192:195], v[106:109]
	v_mfma_f32_16x16x32_bf16 v[94:97], v[152:155], v[200:203], v[94:97]
	v_mfma_f32_16x16x32_bf16 v[90:93], v[160:163], v[200:203], v[90:93]
	v_mfma_f32_16x16x32_bf16 v[78:81], v[152:155], v[208:211], v[78:81]
	v_mfma_f32_16x16x32_bf16 v[74:77], v[160:163], v[208:211], v[74:77]
	s_setprio 0
	s_setprio 1
	v_mfma_f32_16x16x32_bf16 v[118:121], v[164:167], v[180:183], v[118:121]
	v_mfma_f32_16x16x32_bf16 v[114:117], v[172:175], v[180:183], v[114:117]
	v_mfma_f32_16x16x32_bf16 v[102:105], v[164:167], v[188:191], v[102:105]
	v_mfma_f32_16x16x32_bf16 v[98:101], v[172:175], v[188:191], v[98:101]
	v_mfma_f32_16x16x32_bf16 v[86:89], v[164:167], v[196:199], v[86:89]
	v_mfma_f32_16x16x32_bf16 v[82:85], v[172:175], v[196:199], v[82:85]
	v_mfma_f32_16x16x32_bf16 v[70:73], v[164:167], v[204:207], v[70:73]
	v_mfma_f32_16x16x32_bf16 v[66:69], v[172:175], v[204:207], v[66:69]
	v_mfma_f32_16x16x32_bf16 v[118:121], v[168:171], v[184:187], v[118:121]
	v_mfma_f32_16x16x32_bf16 v[114:117], v[176:179], v[184:187], v[114:117]
	v_mfma_f32_16x16x32_bf16 v[102:105], v[168:171], v[192:195], v[102:105]
	v_mfma_f32_16x16x32_bf16 v[98:101], v[176:179], v[192:195], v[98:101]
	v_mfma_f32_16x16x32_bf16 v[86:89], v[168:171], v[200:203], v[86:89]
	v_mfma_f32_16x16x32_bf16 v[82:85], v[176:179], v[200:203], v[82:85]
	v_mfma_f32_16x16x32_bf16 v[70:73], v[168:171], v[208:211], v[70:73]
	v_mfma_f32_16x16x32_bf16 v[66:69], v[176:179], v[208:211], v[66:69]
	s_setprio 0
	s_barrier
	s_add_i32 s18, s42, s29
	v_lshl_add_u64 v[212:213], s[22:23], 0, v[130:131]
	s_mov_b32 m0, s18
	s_nop 0
	global_load_lds_dwordx4 v[212:213], off
	s_add_i32 m0, s18, 0x2000
	s_add_u32 s18, s22, 0x160000
	v_lshl_add_u64 v[214:215], s[22:23], 0, v[132:133]
	s_addc_u32 s19, s23, 0
	s_add_i32 s50, s43, s29
	global_load_lds_dwordx4 v[214:215], off
	v_lshl_add_u64 v[216:217], s[18:19], 0, v[130:131]
	s_mov_b32 m0, s50
	v_lshl_add_u64 v[218:219], s[24:25], 0, v[132:133]
	global_load_lds_dwordx4 v[216:217], off
	v_lshl_add_u64 v[216:217], s[18:19], 0, v[132:133]
	s_add_i32 m0, s50, 0x2000
	s_nop 0
	global_load_lds_dwordx4 v[216:217], off
	v_lshl_add_u64 v[216:217], s[24:25], 0, v[130:131]
	s_mov_b32 m0, s30
	s_nop 0
	global_load_lds_dwordx4 v[216:217], off
	s_mov_b32 m0, s31
	s_nop 0
	global_load_lds_dwordx4 v[218:219], off
	ds_read_b128 v[180:183], v150 offset:16384
	ds_read_b128 v[184:187], v150 offset:17408
	ds_read_b128 v[188:191], v150 offset:18432
	ds_read_b128 v[192:195], v150 offset:19456
	ds_read_b128 v[196:199], v150 offset:20480
	ds_read_b128 v[200:203], v150 offset:21504
	ds_read_b128 v[204:207], v150 offset:22528
	ds_read_b128 v[208:211], v150 offset:23552
	s_waitcnt vmcnt(8)
	s_waitcnt lgkmcnt(0)
	s_barrier
	s_setprio 1
	s_waitcnt lgkmcnt(0)
	v_mfma_f32_16x16x32_bf16 v[62:65], v[142:145], v[180:183], v[62:65]
	v_mfma_f32_16x16x32_bf16 v[58:61], v[156:159], v[180:183], v[58:61]
	v_mfma_f32_16x16x32_bf16 v[46:49], v[142:145], v[188:191], v[46:49]
	v_mfma_f32_16x16x32_bf16 v[42:45], v[156:159], v[188:191], v[42:45]
	v_mfma_f32_16x16x32_bf16 v[30:33], v[142:145], v[196:199], v[30:33]
	v_mfma_f32_16x16x32_bf16 v[26:29], v[156:159], v[196:199], v[26:29]
	v_mfma_f32_16x16x32_bf16 v[14:17], v[142:145], v[204:207], v[14:17]
	v_mfma_f32_16x16x32_bf16 v[10:13], v[156:159], v[204:207], v[10:13]
	v_mfma_f32_16x16x32_bf16 v[62:65], v[152:155], v[184:187], v[62:65]
	v_mfma_f32_16x16x32_bf16 v[58:61], v[160:163], v[184:187], v[58:61]
	v_mfma_f32_16x16x32_bf16 v[46:49], v[152:155], v[192:195], v[46:49]
	v_mfma_f32_16x16x32_bf16 v[42:45], v[160:163], v[192:195], v[42:45]
	v_mfma_f32_16x16x32_bf16 v[30:33], v[152:155], v[200:203], v[30:33]
	v_mfma_f32_16x16x32_bf16 v[26:29], v[160:163], v[200:203], v[26:29]
	v_mfma_f32_16x16x32_bf16 v[14:17], v[152:155], v[208:211], v[14:17]
	v_mfma_f32_16x16x32_bf16 v[10:13], v[160:163], v[208:211], v[10:13]
	s_setprio 0
	s_setprio 1
	v_mfma_f32_16x16x32_bf16 v[54:57], v[164:167], v[180:183], v[54:57]
	v_mfma_f32_16x16x32_bf16 v[50:53], v[172:175], v[180:183], v[50:53]
	v_mfma_f32_16x16x32_bf16 v[38:41], v[164:167], v[188:191], v[38:41]
	v_mfma_f32_16x16x32_bf16 v[34:37], v[172:175], v[188:191], v[34:37]
	v_mfma_f32_16x16x32_bf16 v[22:25], v[164:167], v[196:199], v[22:25]
	v_mfma_f32_16x16x32_bf16 v[18:21], v[172:175], v[196:199], v[18:21]
	v_mfma_f32_16x16x32_bf16 v[6:9], v[164:167], v[204:207], v[6:9]
	v_mfma_f32_16x16x32_bf16 v[2:5], v[172:175], v[204:207], v[2:5]
	v_mfma_f32_16x16x32_bf16 v[54:57], v[168:171], v[184:187], v[54:57]
	v_mfma_f32_16x16x32_bf16 v[50:53], v[176:179], v[184:187], v[50:53]
	v_mfma_f32_16x16x32_bf16 v[38:41], v[168:171], v[192:195], v[38:41]
	v_mfma_f32_16x16x32_bf16 v[34:37], v[176:179], v[192:195], v[34:37]
	v_mfma_f32_16x16x32_bf16 v[22:25], v[168:171], v[200:203], v[22:25]
	v_mfma_f32_16x16x32_bf16 v[18:21], v[176:179], v[200:203], v[18:21]
	v_mfma_f32_16x16x32_bf16 v[6:9], v[168:171], v[208:211], v[6:9]
	v_mfma_f32_16x16x32_bf16 v[2:5], v[176:179], v[208:211], v[2:5]
	s_setprio 0
	s_barrier
	s_add_i32 s50, 0, 0x18000
	s_add_i32 s51, 0, 0x1c000
	s_add_u32 s18, s24, 0x160000
	s_addc_u32 s19, s25, 0
	s_mov_b32 m0, s33
	v_lshl_add_u64 v[220:221], s[18:19], 0, v[130:131]
	global_load_lds_dwordx4 v[220:221], off
	v_lshl_add_u64 v[220:221], s[18:19], 0, v[132:133]
	s_mov_b32 m0, s34
	s_nop 0
	global_load_lds_dwordx4 v[220:221], off
	v_add_u32_e32 v160, s50, v147
	v_add_u32_e32 v176, s51, v147
	ds_read_b128 v[142:145], v160
	ds_read_b128 v[152:155], v160 offset:1024
	ds_read_b128 v[156:159], v160 offset:2048
	ds_read_b128 v[160:163], v160 offset:3072
	ds_read_b128 v[164:167], v176
	ds_read_b128 v[168:171], v176 offset:1024
	ds_read_b128 v[172:175], v176 offset:2048
	ds_read_b128 v[176:179], v176 offset:3072
	ds_read_b128 v[180:183], v150 offset:32768
	ds_read_b128 v[184:187], v150 offset:33792
	ds_read_b128 v[188:191], v150 offset:34816
	ds_read_b128 v[192:195], v150 offset:35840
	ds_read_b128 v[196:199], v150 offset:36864
	ds_read_b128 v[200:203], v150 offset:37888
	ds_read_b128 v[204:207], v150 offset:38912
	ds_read_b128 v[208:211], v150 offset:39936
	s_waitcnt vmcnt(8)
	s_waitcnt lgkmcnt(0)
	s_barrier
	s_setprio 1
	s_waitcnt lgkmcnt(0)
	v_mfma_f32_16x16x32_bf16 v[126:129], v[142:145], v[180:183], v[126:129]
	v_mfma_f32_16x16x32_bf16 v[122:125], v[156:159], v[180:183], v[122:125]
	v_mfma_f32_16x16x32_bf16 v[110:113], v[142:145], v[188:191], v[110:113]
	v_mfma_f32_16x16x32_bf16 v[106:109], v[156:159], v[188:191], v[106:109]
	v_mfma_f32_16x16x32_bf16 v[94:97], v[142:145], v[196:199], v[94:97]
	v_mfma_f32_16x16x32_bf16 v[90:93], v[156:159], v[196:199], v[90:93]
	v_mfma_f32_16x16x32_bf16 v[78:81], v[142:145], v[204:207], v[78:81]
	v_mfma_f32_16x16x32_bf16 v[74:77], v[156:159], v[204:207], v[74:77]
	v_mfma_f32_16x16x32_bf16 v[126:129], v[152:155], v[184:187], v[126:129]
	v_mfma_f32_16x16x32_bf16 v[122:125], v[160:163], v[184:187], v[122:125]
	v_mfma_f32_16x16x32_bf16 v[110:113], v[152:155], v[192:195], v[110:113]
	v_mfma_f32_16x16x32_bf16 v[106:109], v[160:163], v[192:195], v[106:109]
	v_mfma_f32_16x16x32_bf16 v[94:97], v[152:155], v[200:203], v[94:97]
	v_mfma_f32_16x16x32_bf16 v[90:93], v[160:163], v[200:203], v[90:93]
	v_mfma_f32_16x16x32_bf16 v[78:81], v[152:155], v[208:211], v[78:81]
	v_mfma_f32_16x16x32_bf16 v[74:77], v[160:163], v[208:211], v[74:77]
	s_setprio 0
	s_setprio 1
	v_mfma_f32_16x16x32_bf16 v[118:121], v[164:167], v[180:183], v[118:121]
	v_mfma_f32_16x16x32_bf16 v[114:117], v[172:175], v[180:183], v[114:117]
	v_mfma_f32_16x16x32_bf16 v[102:105], v[164:167], v[188:191], v[102:105]
	v_mfma_f32_16x16x32_bf16 v[98:101], v[172:175], v[188:191], v[98:101]
	v_mfma_f32_16x16x32_bf16 v[86:89], v[164:167], v[196:199], v[86:89]
	v_mfma_f32_16x16x32_bf16 v[82:85], v[172:175], v[196:199], v[82:85]
	v_mfma_f32_16x16x32_bf16 v[70:73], v[164:167], v[204:207], v[70:73]
	v_mfma_f32_16x16x32_bf16 v[66:69], v[172:175], v[204:207], v[66:69]
	v_mfma_f32_16x16x32_bf16 v[118:121], v[168:171], v[184:187], v[118:121]
	v_mfma_f32_16x16x32_bf16 v[114:117], v[176:179], v[184:187], v[114:117]
	v_mfma_f32_16x16x32_bf16 v[102:105], v[168:171], v[192:195], v[102:105]
	v_mfma_f32_16x16x32_bf16 v[98:101], v[176:179], v[192:195], v[98:101]
	v_mfma_f32_16x16x32_bf16 v[86:89], v[168:171], v[200:203], v[86:89]
	v_mfma_f32_16x16x32_bf16 v[82:85], v[176:179], v[200:203], v[82:85]
	v_mfma_f32_16x16x32_bf16 v[70:73], v[168:171], v[208:211], v[70:73]
	v_mfma_f32_16x16x32_bf16 v[66:69], v[176:179], v[208:211], v[66:69]
	s_setprio 0
	s_barrier
	s_add_i32 s18, s50, s29
	v_lshl_add_u64 v[212:213], v[212:213], 0, s[12:13]
	s_mov_b32 m0, s18
	s_nop 0
	global_load_lds_dwordx4 v[212:213], off
	s_add_i32 m0, s18, 0x2000
	s_add_u32 s18, s22, 0x160080
	v_lshl_add_u64 v[212:213], v[214:215], 0, s[12:13]
	s_addc_u32 s19, s23, 0
	s_add_i32 s22, s51, s29
	global_load_lds_dwordx4 v[212:213], off
	v_lshl_add_u64 v[212:213], s[18:19], 0, v[130:131]
	s_mov_b32 m0, s22
	s_nop 0
	global_load_lds_dwordx4 v[212:213], off
	v_lshl_add_u64 v[212:213], s[18:19], 0, v[132:133]
	s_add_i32 m0, s22, 0x2000
	s_nop 0
	global_load_lds_dwordx4 v[212:213], off
	v_lshl_add_u64 v[212:213], v[216:217], 0, s[12:13]
	s_mov_b32 m0, s38
	s_nop 0
	global_load_lds_dwordx4 v[212:213], off
	v_lshl_add_u64 v[212:213], v[218:219], 0, s[12:13]
	s_mov_b32 m0, s39
	s_nop 0
	global_load_lds_dwordx4 v[212:213], off
	ds_read_b128 v[180:183], v150 offset:49152
	ds_read_b128 v[184:187], v150 offset:50176
	ds_read_b128 v[188:191], v150 offset:51200
	ds_read_b128 v[192:195], v150 offset:52224
	ds_read_b128 v[196:199], v150 offset:53248
	ds_read_b128 v[200:203], v150 offset:54272
	ds_read_b128 v[204:207], v150 offset:55296
	ds_read_b128 v[208:211], v150 offset:56320
	s_waitcnt vmcnt(8)
	s_waitcnt lgkmcnt(0)
	s_barrier
	s_setprio 1
	s_waitcnt lgkmcnt(0)
	v_mfma_f32_16x16x32_bf16 v[62:65], v[142:145], v[180:183], v[62:65]
	v_mfma_f32_16x16x32_bf16 v[58:61], v[156:159], v[180:183], v[58:61]
	v_mfma_f32_16x16x32_bf16 v[46:49], v[142:145], v[188:191], v[46:49]
	v_mfma_f32_16x16x32_bf16 v[42:45], v[156:159], v[188:191], v[42:45]
	v_mfma_f32_16x16x32_bf16 v[30:33], v[142:145], v[196:199], v[30:33]
	v_mfma_f32_16x16x32_bf16 v[26:29], v[156:159], v[196:199], v[26:29]
	v_mfma_f32_16x16x32_bf16 v[14:17], v[142:145], v[204:207], v[14:17]
	v_mfma_f32_16x16x32_bf16 v[10:13], v[156:159], v[204:207], v[10:13]
	v_mfma_f32_16x16x32_bf16 v[62:65], v[152:155], v[184:187], v[62:65]
	v_mfma_f32_16x16x32_bf16 v[58:61], v[160:163], v[184:187], v[58:61]
	v_mfma_f32_16x16x32_bf16 v[46:49], v[152:155], v[192:195], v[46:49]
	v_mfma_f32_16x16x32_bf16 v[42:45], v[160:163], v[192:195], v[42:45]
	v_mfma_f32_16x16x32_bf16 v[30:33], v[152:155], v[200:203], v[30:33]
	v_mfma_f32_16x16x32_bf16 v[26:29], v[160:163], v[200:203], v[26:29]
	v_mfma_f32_16x16x32_bf16 v[14:17], v[152:155], v[208:211], v[14:17]
	v_mfma_f32_16x16x32_bf16 v[10:13], v[160:163], v[208:211], v[10:13]
	s_setprio 0
	s_setprio 1
	v_mfma_f32_16x16x32_bf16 v[54:57], v[164:167], v[180:183], v[54:57]
	v_mfma_f32_16x16x32_bf16 v[50:53], v[172:175], v[180:183], v[50:53]
	v_mfma_f32_16x16x32_bf16 v[38:41], v[164:167], v[188:191], v[38:41]
	v_mfma_f32_16x16x32_bf16 v[34:37], v[172:175], v[188:191], v[34:37]
	v_mfma_f32_16x16x32_bf16 v[22:25], v[164:167], v[196:199], v[22:25]
	v_mfma_f32_16x16x32_bf16 v[18:21], v[172:175], v[196:199], v[18:21]
	v_mfma_f32_16x16x32_bf16 v[6:9], v[164:167], v[204:207], v[6:9]
	v_mfma_f32_16x16x32_bf16 v[2:5], v[172:175], v[204:207], v[2:5]
	v_mfma_f32_16x16x32_bf16 v[54:57], v[168:171], v[184:187], v[54:57]
	v_mfma_f32_16x16x32_bf16 v[50:53], v[176:179], v[184:187], v[50:53]
	v_mfma_f32_16x16x32_bf16 v[38:41], v[168:171], v[192:195], v[38:41]
	v_mfma_f32_16x16x32_bf16 v[34:37], v[176:179], v[192:195], v[34:37]
	v_mfma_f32_16x16x32_bf16 v[22:25], v[168:171], v[200:203], v[22:25]
	v_mfma_f32_16x16x32_bf16 v[18:21], v[176:179], v[200:203], v[18:21]
	v_mfma_f32_16x16x32_bf16 v[6:9], v[168:171], v[208:211], v[6:9]
	v_mfma_f32_16x16x32_bf16 v[2:5], v[176:179], v[208:211], v[2:5]
	s_setprio 0
	s_barrier
	s_add_i32 s49, s49, 2
	s_add_u32 s47, s47, 0x100
	s_addc_u32 s48, s48, 0
	s_cmpk_gt_u32 s49, 0x55
	s_mov_b64 s[18:19], s[20:21]
	s_cbranch_scc0 .LBB0_2118
	s_and_b64 vcc, exec, s[14:15]
	s_cbranch_vccz .LBB0_2121
	s_barrier

.LBB0_2207:
	s_add_u32 s28, s10, 0xfff80080
	s_addc_u32 s29, s11, -1
	s_cmp_eq_u32 s36, 28
	s_cselect_b32 s31, s7, s29
	s_cselect_b32 s30, s9, s28
	s_cselect_b32 s29, s21, s35
	s_cselect_b32 s28, s23, s34
	v_lshl_add_u64 v[194:195], s[10:11], 0, v[184:185]
	s_add_i32 m0, s39, 0xc000
	s_nop 0
	global_load_lds_dwordx4 v[194:195], off
	v_lshl_add_u64 v[194:195], s[10:11], 0, v[186:187]
	s_add_i32 m0, s39, 0xe000
	s_nop 0
	global_load_lds_dwordx4 v[194:195], off
	ds_read_b128 v[130:133], v197
	ds_read_b128 v[134:137], v197 offset:1024
	ds_read_b128 v[138:141], v197 offset:2048
	ds_read_b128 v[142:145], v197 offset:3072
	ds_read_b128 v[146:149], v198
	ds_read_b128 v[150:153], v198 offset:1024
	ds_read_b128 v[154:157], v198 offset:2048
	ds_read_b128 v[158:161], v198 offset:3072
	ds_read_b128 v[162:165], v199
	ds_read_b128 v[166:169], v199 offset:1024
	ds_read_b128 v[170:173], v199 offset:2048
	ds_read_b128 v[174:177], v199 offset:3072
	ds_read_b128 v[202:205], v199 offset:4096
	ds_read_b128 v[206:209], v199 offset:5120
	ds_read_b128 v[210:213], v199 offset:6144
	ds_read_b128 v[214:217], v199 offset:7168
	s_waitcnt vmcnt(8)
	s_waitcnt lgkmcnt(0)
	s_barrier
	s_setprio 1
	s_waitcnt lgkmcnt(0)
	v_mfma_f32_16x16x32_bf16 v[126:129], v[130:133], v[162:165], v[126:129]
	v_mfma_f32_16x16x32_bf16 v[122:125], v[138:141], v[162:165], v[122:125]
	v_mfma_f32_16x16x32_bf16 v[110:113], v[130:133], v[170:173], v[110:113]
	v_mfma_f32_16x16x32_bf16 v[106:109], v[138:141], v[170:173], v[106:109]
	v_mfma_f32_16x16x32_bf16 v[94:97], v[130:133], v[202:205], v[94:97]
	v_mfma_f32_16x16x32_bf16 v[90:93], v[138:141], v[202:205], v[90:93]
	v_mfma_f32_16x16x32_bf16 v[78:81], v[130:133], v[210:213], v[78:81]
	v_mfma_f32_16x16x32_bf16 v[74:77], v[138:141], v[210:213], v[74:77]
	v_mfma_f32_16x16x32_bf16 v[126:129], v[134:137], v[166:169], v[126:129]
	v_mfma_f32_16x16x32_bf16 v[122:125], v[142:145], v[166:169], v[122:125]
	v_mfma_f32_16x16x32_bf16 v[110:113], v[134:137], v[174:177], v[110:113]
	v_mfma_f32_16x16x32_bf16 v[106:109], v[142:145], v[174:177], v[106:109]
	v_mfma_f32_16x16x32_bf16 v[94:97], v[134:137], v[206:209], v[94:97]
	v_mfma_f32_16x16x32_bf16 v[90:93], v[142:145], v[206:209], v[90:93]
	v_mfma_f32_16x16x32_bf16 v[78:81], v[134:137], v[214:217], v[78:81]
	v_mfma_f32_16x16x32_bf16 v[74:77], v[142:145], v[214:217], v[74:77]
	s_setprio 0
	s_setprio 1
	v_mfma_f32_16x16x32_bf16 v[118:121], v[146:149], v[162:165], v[118:121]
	v_mfma_f32_16x16x32_bf16 v[114:117], v[154:157], v[162:165], v[114:117]
	v_mfma_f32_16x16x32_bf16 v[102:105], v[146:149], v[170:173], v[102:105]
	v_mfma_f32_16x16x32_bf16 v[98:101], v[154:157], v[170:173], v[98:101]
	v_mfma_f32_16x16x32_bf16 v[86:89], v[146:149], v[202:205], v[86:89]
	v_mfma_f32_16x16x32_bf16 v[82:85], v[154:157], v[202:205], v[82:85]
	v_mfma_f32_16x16x32_bf16 v[70:73], v[146:149], v[210:213], v[70:73]
	v_mfma_f32_16x16x32_bf16 v[66:69], v[154:157], v[210:213], v[66:69]
	v_mfma_f32_16x16x32_bf16 v[118:121], v[150:153], v[166:169], v[118:121]
	v_mfma_f32_16x16x32_bf16 v[114:117], v[158:161], v[166:169], v[114:117]
	v_mfma_f32_16x16x32_bf16 v[102:105], v[150:153], v[174:177], v[102:105]
	v_mfma_f32_16x16x32_bf16 v[98:101], v[158:161], v[174:177], v[98:101]
	v_mfma_f32_16x16x32_bf16 v[86:89], v[150:153], v[206:209], v[86:89]
	v_mfma_f32_16x16x32_bf16 v[82:85], v[158:161], v[206:209], v[82:85]
	v_mfma_f32_16x16x32_bf16 v[70:73], v[150:153], v[214:217], v[70:73]
	v_mfma_f32_16x16x32_bf16 v[66:69], v[158:161], v[214:217], v[66:69]
	s_setprio 0
	s_barrier
	s_add_i32 s37, s52, s38
	v_lshl_add_u64 v[194:195], s[28:29], 0, v[178:179]
	s_mov_b32 m0, s37
	s_nop 0
	global_load_lds_dwordx4 v[194:195], off
	s_add_i32 m0, s37, 0x2000
	s_add_u32 s56, s28, 0x80000
	v_lshl_add_u64 v[218:219], s[28:29], 0, v[180:181]
	s_addc_u32 s57, s29, 0
	s_add_i32 s37, s53, s38
	global_load_lds_dwordx4 v[218:219], off
	v_lshl_add_u64 v[220:221], s[56:57], 0, v[178:179]
	s_mov_b32 m0, s37
	v_lshl_add_u64 v[222:223], s[30:31], 0, v[180:181]
	global_load_lds_dwordx4 v[220:221], off
	v_lshl_add_u64 v[220:221], s[56:57], 0, v[180:181]
	s_add_i32 m0, s37, 0x2000
	s_nop 0
	global_load_lds_dwordx4 v[220:221], off
	v_lshl_add_u64 v[220:221], s[30:31], 0, v[178:179]
	s_mov_b32 m0, s39
	s_nop 0
	global_load_lds_dwordx4 v[220:221], off
	s_mov_b32 m0, s40
	s_nop 0
	global_load_lds_dwordx4 v[222:223], off
	ds_read_b128 v[162:165], v199 offset:16384
	ds_read_b128 v[166:169], v199 offset:17408
	ds_read_b128 v[170:173], v199 offset:18432
	ds_read_b128 v[174:177], v199 offset:19456
	ds_read_b128 v[202:205], v199 offset:20480
	ds_read_b128 v[206:209], v199 offset:21504
	ds_read_b128 v[210:213], v199 offset:22528
	ds_read_b128 v[214:217], v199 offset:23552
	s_waitcnt vmcnt(8)
	s_waitcnt lgkmcnt(0)
	s_barrier
	s_setprio 1
	s_waitcnt lgkmcnt(0)
	v_mfma_f32_16x16x32_bf16 v[62:65], v[130:133], v[162:165], v[62:65]
	v_mfma_f32_16x16x32_bf16 v[58:61], v[138:141], v[162:165], v[58:61]
	v_mfma_f32_16x16x32_bf16 v[46:49], v[130:133], v[170:173], v[46:49]
	v_mfma_f32_16x16x32_bf16 v[42:45], v[138:141], v[170:173], v[42:45]
	v_mfma_f32_16x16x32_bf16 v[30:33], v[130:133], v[202:205], v[30:33]
	v_mfma_f32_16x16x32_bf16 v[26:29], v[138:141], v[202:205], v[26:29]
	v_mfma_f32_16x16x32_bf16 v[14:17], v[130:133], v[210:213], v[14:17]
	v_mfma_f32_16x16x32_bf16 v[10:13], v[138:141], v[210:213], v[10:13]
	v_mfma_f32_16x16x32_bf16 v[62:65], v[134:137], v[166:169], v[62:65]
	v_mfma_f32_16x16x32_bf16 v[58:61], v[142:145], v[166:169], v[58:61]
	v_mfma_f32_16x16x32_bf16 v[46:49], v[134:137], v[174:177], v[46:49]
	v_mfma_f32_16x16x32_bf16 v[42:45], v[142:145], v[174:177], v[42:45]
	v_mfma_f32_16x16x32_bf16 v[30:33], v[134:137], v[206:209], v[30:33]
	v_mfma_f32_16x16x32_bf16 v[26:29], v[142:145], v[206:209], v[26:29]
	v_mfma_f32_16x16x32_bf16 v[14:17], v[134:137], v[214:217], v[14:17]
	v_mfma_f32_16x16x32_bf16 v[10:13], v[142:145], v[214:217], v[10:13]
	s_setprio 0
	s_setprio 1
	v_mfma_f32_16x16x32_bf16 v[54:57], v[146:149], v[162:165], v[54:57]
	v_mfma_f32_16x16x32_bf16 v[50:53], v[154:157], v[162:165], v[50:53]
	v_mfma_f32_16x16x32_bf16 v[38:41], v[146:149], v[170:173], v[38:41]
	v_mfma_f32_16x16x32_bf16 v[34:37], v[154:157], v[170:173], v[34:37]
	v_mfma_f32_16x16x32_bf16 v[22:25], v[146:149], v[202:205], v[22:25]
	v_mfma_f32_16x16x32_bf16 v[18:21], v[154:157], v[202:205], v[18:21]
	v_mfma_f32_16x16x32_bf16 v[6:9], v[146:149], v[210:213], v[6:9]
	v_mfma_f32_16x16x32_bf16 v[2:5], v[154:157], v[210:213], v[2:5]
	v_mfma_f32_16x16x32_bf16 v[54:57], v[150:153], v[166:169], v[54:57]
	v_mfma_f32_16x16x32_bf16 v[50:53], v[158:161], v[166:169], v[50:53]
	v_mfma_f32_16x16x32_bf16 v[38:41], v[150:153], v[174:177], v[38:41]
	v_mfma_f32_16x16x32_bf16 v[34:37], v[158:161], v[174:177], v[34:37]
	v_mfma_f32_16x16x32_bf16 v[22:25], v[150:153], v[206:209], v[22:25]
	v_mfma_f32_16x16x32_bf16 v[18:21], v[158:161], v[206:209], v[18:21]
	v_mfma_f32_16x16x32_bf16 v[6:9], v[150:153], v[214:217], v[6:9]
	v_mfma_f32_16x16x32_bf16 v[2:5], v[158:161], v[214:217], v[2:5]
	s_setprio 0
	s_barrier
	s_add_i32 s37, 0, 0x18000
	s_add_i32 s56, 0, 0x1c000
	s_add_u32 s30, s30, 0x80000
	s_addc_u32 s31, s31, 0
	s_mov_b32 m0, s41
	v_lshl_add_u64 v[224:225], s[30:31], 0, v[178:179]
	global_load_lds_dwordx4 v[224:225], off
	v_lshl_add_u64 v[224:225], s[30:31], 0, v[180:181]
	s_mov_b32 m0, s42
	s_nop 0
	global_load_lds_dwordx4 v[224:225], off
	v_add_u32_e32 v142, s37, v196
	v_add_u32_e32 v158, s56, v196
	ds_read_b128 v[130:133], v142
	ds_read_b128 v[134:137], v142 offset:1024
	ds_read_b128 v[138:141], v142 offset:2048
	ds_read_b128 v[142:145], v142 offset:3072
	ds_read_b128 v[146:149], v158
	ds_read_b128 v[150:153], v158 offset:1024
	ds_read_b128 v[154:157], v158 offset:2048
	ds_read_b128 v[158:161], v158 offset:3072
	ds_read_b128 v[162:165], v199 offset:32768
	ds_read_b128 v[166:169], v199 offset:33792
	ds_read_b128 v[170:173], v199 offset:34816
	ds_read_b128 v[174:177], v199 offset:35840
	ds_read_b128 v[202:205], v199 offset:36864
	ds_read_b128 v[206:209], v199 offset:37888
	ds_read_b128 v[210:213], v199 offset:38912
	ds_read_b128 v[214:217], v199 offset:39936
	s_waitcnt vmcnt(8)
	s_waitcnt lgkmcnt(0)
	s_barrier
	s_setprio 1
	s_waitcnt lgkmcnt(0)
	v_mfma_f32_16x16x32_bf16 v[126:129], v[130:133], v[162:165], v[126:129]
	v_mfma_f32_16x16x32_bf16 v[122:125], v[138:141], v[162:165], v[122:125]
	v_mfma_f32_16x16x32_bf16 v[110:113], v[130:133], v[170:173], v[110:113]
	v_mfma_f32_16x16x32_bf16 v[106:109], v[138:141], v[170:173], v[106:109]
	v_mfma_f32_16x16x32_bf16 v[94:97], v[130:133], v[202:205], v[94:97]
	v_mfma_f32_16x16x32_bf16 v[90:93], v[138:141], v[202:205], v[90:93]
	v_mfma_f32_16x16x32_bf16 v[78:81], v[130:133], v[210:213], v[78:81]
	v_mfma_f32_16x16x32_bf16 v[74:77], v[138:141], v[210:213], v[74:77]
	v_mfma_f32_16x16x32_bf16 v[126:129], v[134:137], v[166:169], v[126:129]
	v_mfma_f32_16x16x32_bf16 v[122:125], v[142:145], v[166:169], v[122:125]
	v_mfma_f32_16x16x32_bf16 v[110:113], v[134:137], v[174:177], v[110:113]
	v_mfma_f32_16x16x32_bf16 v[106:109], v[142:145], v[174:177], v[106:109]
	v_mfma_f32_16x16x32_bf16 v[94:97], v[134:137], v[206:209], v[94:97]
	v_mfma_f32_16x16x32_bf16 v[90:93], v[142:145], v[206:209], v[90:93]
	v_mfma_f32_16x16x32_bf16 v[78:81], v[134:137], v[214:217], v[78:81]
	v_mfma_f32_16x16x32_bf16 v[74:77], v[142:145], v[214:217], v[74:77]
	s_setprio 0
	s_setprio 1
	v_mfma_f32_16x16x32_bf16 v[118:121], v[146:149], v[162:165], v[118:121]
	v_mfma_f32_16x16x32_bf16 v[114:117], v[154:157], v[162:165], v[114:117]
	v_mfma_f32_16x16x32_bf16 v[102:105], v[146:149], v[170:173], v[102:105]
	v_mfma_f32_16x16x32_bf16 v[98:101], v[154:157], v[170:173], v[98:101]
	v_mfma_f32_16x16x32_bf16 v[86:89], v[146:149], v[202:205], v[86:89]
	v_mfma_f32_16x16x32_bf16 v[82:85], v[154:157], v[202:205], v[82:85]
	v_mfma_f32_16x16x32_bf16 v[70:73], v[146:149], v[210:213], v[70:73]
	v_mfma_f32_16x16x32_bf16 v[66:69], v[154:157], v[210:213], v[66:69]
	v_mfma_f32_16x16x32_bf16 v[118:121], v[150:153], v[166:169], v[118:121]
	v_mfma_f32_16x16x32_bf16 v[114:117], v[158:161], v[166:169], v[114:117]
	v_mfma_f32_16x16x32_bf16 v[102:105], v[150:153], v[174:177], v[102:105]
	v_mfma_f32_16x16x32_bf16 v[98:101], v[158:161], v[174:177], v[98:101]
	v_mfma_f32_16x16x32_bf16 v[86:89], v[150:153], v[206:209], v[86:89]
	v_mfma_f32_16x16x32_bf16 v[82:85], v[158:161], v[206:209], v[82:85]
	v_mfma_f32_16x16x32_bf16 v[70:73], v[150:153], v[214:217], v[70:73]
	v_mfma_f32_16x16x32_bf16 v[66:69], v[158:161], v[214:217], v[66:69]
	s_setprio 0
	s_barrier
	s_add_i32 s30, s37, s38
	v_lshl_add_u64 v[194:195], v[194:195], 0, s[14:15]
	s_mov_b32 m0, s30
	s_nop 0
	global_load_lds_dwordx4 v[194:195], off
	s_add_i32 m0, s30, 0x2000
	s_add_u32 s28, s28, 0x80080
	v_lshl_add_u64 v[194:195], v[218:219], 0, s[14:15]
	s_addc_u32 s29, s29, 0
	s_add_i32 s30, s56, s38
	global_load_lds_dwordx4 v[194:195], off
	v_lshl_add_u64 v[194:195], s[28:29], 0, v[178:179]
	s_mov_b32 m0, s30
	s_nop 0
	global_load_lds_dwordx4 v[194:195], off
	v_lshl_add_u64 v[194:195], s[28:29], 0, v[180:181]
	s_add_i32 m0, s30, 0x2000
	s_nop 0
	global_load_lds_dwordx4 v[194:195], off
	v_lshl_add_u64 v[194:195], v[220:221], 0, s[14:15]
	s_mov_b32 m0, s46
	s_nop 0
	global_load_lds_dwordx4 v[194:195], off
	v_lshl_add_u64 v[194:195], v[222:223], 0, s[14:15]
	s_mov_b32 m0, s47
	s_nop 0
	global_load_lds_dwordx4 v[194:195], off
	ds_read_b128 v[162:165], v199 offset:49152
	ds_read_b128 v[166:169], v199 offset:50176
	ds_read_b128 v[170:173], v199 offset:51200
	ds_read_b128 v[174:177], v199 offset:52224
	ds_read_b128 v[202:205], v199 offset:53248
	ds_read_b128 v[206:209], v199 offset:54272
	ds_read_b128 v[210:213], v199 offset:55296
	ds_read_b128 v[214:217], v199 offset:56320
	s_waitcnt vmcnt(8)
	s_waitcnt lgkmcnt(0)
	s_barrier
	s_setprio 1
	s_waitcnt lgkmcnt(0)
	v_mfma_f32_16x16x32_bf16 v[62:65], v[130:133], v[162:165], v[62:65]
	v_mfma_f32_16x16x32_bf16 v[58:61], v[138:141], v[162:165], v[58:61]
	v_mfma_f32_16x16x32_bf16 v[46:49], v[130:133], v[170:173], v[46:49]
	v_mfma_f32_16x16x32_bf16 v[42:45], v[138:141], v[170:173], v[42:45]
	v_mfma_f32_16x16x32_bf16 v[30:33], v[130:133], v[202:205], v[30:33]
	v_mfma_f32_16x16x32_bf16 v[26:29], v[138:141], v[202:205], v[26:29]
	v_mfma_f32_16x16x32_bf16 v[14:17], v[130:133], v[210:213], v[14:17]
	v_mfma_f32_16x16x32_bf16 v[10:13], v[138:141], v[210:213], v[10:13]
	v_mfma_f32_16x16x32_bf16 v[62:65], v[134:137], v[166:169], v[62:65]
	v_mfma_f32_16x16x32_bf16 v[58:61], v[142:145], v[166:169], v[58:61]
	v_mfma_f32_16x16x32_bf16 v[46:49], v[134:137], v[174:177], v[46:49]
	v_mfma_f32_16x16x32_bf16 v[42:45], v[142:145], v[174:177], v[42:45]
	v_mfma_f32_16x16x32_bf16 v[30:33], v[134:137], v[206:209], v[30:33]
	v_mfma_f32_16x16x32_bf16 v[26:29], v[142:145], v[206:209], v[26:29]
	v_mfma_f32_16x16x32_bf16 v[14:17], v[134:137], v[214:217], v[14:17]
	v_mfma_f32_16x16x32_bf16 v[10:13], v[142:145], v[214:217], v[10:13]
	s_setprio 0
	s_setprio 1
	v_mfma_f32_16x16x32_bf16 v[54:57], v[146:149], v[162:165], v[54:57]
	v_mfma_f32_16x16x32_bf16 v[50:53], v[154:157], v[162:165], v[50:53]
	v_mfma_f32_16x16x32_bf16 v[38:41], v[146:149], v[170:173], v[38:41]
	v_mfma_f32_16x16x32_bf16 v[34:37], v[154:157], v[170:173], v[34:37]
	v_mfma_f32_16x16x32_bf16 v[22:25], v[146:149], v[202:205], v[22:25]
	v_mfma_f32_16x16x32_bf16 v[18:21], v[154:157], v[202:205], v[18:21]
	v_mfma_f32_16x16x32_bf16 v[6:9], v[146:149], v[210:213], v[6:9]
	v_mfma_f32_16x16x32_bf16 v[2:5], v[154:157], v[210:213], v[2:5]
	v_mfma_f32_16x16x32_bf16 v[54:57], v[150:153], v[166:169], v[54:57]
	v_mfma_f32_16x16x32_bf16 v[50:53], v[158:161], v[166:169], v[50:53]
	v_mfma_f32_16x16x32_bf16 v[38:41], v[150:153], v[174:177], v[38:41]
	v_mfma_f32_16x16x32_bf16 v[34:37], v[158:161], v[174:177], v[34:37]
	v_mfma_f32_16x16x32_bf16 v[22:25], v[150:153], v[206:209], v[22:25]
	v_mfma_f32_16x16x32_bf16 v[18:21], v[158:161], v[206:209], v[18:21]
	v_mfma_f32_16x16x32_bf16 v[6:9], v[150:153], v[214:217], v[6:9]
	v_mfma_f32_16x16x32_bf16 v[2:5], v[158:161], v[214:217], v[2:5]
	s_setprio 0
	s_barrier
	s_add_i32 s36, s36, 2
	s_add_u32 s10, s10, 0x100
	s_addc_u32 s11, s11, 0
	s_add_u32 s34, s34, 0x100
	s_addc_u32 s35, s35, 0
	s_cmp_gt_u32 s36, 29
	s_cbranch_scc0 .LBB0_2207
	s_and_b64 vcc, exec, s[16:17]
	s_cbranch_vccz .LBB0_2210
	s_barrier

.LBB0_3114:
	s_add_u32 s26, s24, 0x100
	s_addc_u32 s27, s25, 0
	s_cmp_eq_u32 s55, 28
	s_cselect_b32 s31, s19, s27
	s_cselect_b32 s30, s51, s26
	s_cselect_b32 s29, s17, s54
	s_cselect_b32 s28, s52, s53
	v_lshl_add_u64 v[212:213], s[24:25], 0, v[134:135]
	s_add_i32 m0, s5, 0xc000
	s_nop 0
	global_load_lds_dwordx4 v[212:213], off
	v_lshl_add_u64 v[212:213], s[24:25], 0, v[136:137]
	s_add_i32 m0, s5, 0xe000
	s_nop 0
	global_load_lds_dwordx4 v[212:213], off
	ds_read_b128 v[142:145], v148
	ds_read_b128 v[152:155], v148 offset:1024
	ds_read_b128 v[156:159], v148 offset:2048
	ds_read_b128 v[160:163], v148 offset:3072
	ds_read_b128 v[164:167], v149
	ds_read_b128 v[168:171], v149 offset:1024
	ds_read_b128 v[172:175], v149 offset:2048
	ds_read_b128 v[176:179], v149 offset:3072
	ds_read_b128 v[180:183], v150
	ds_read_b128 v[184:187], v150 offset:1024
	ds_read_b128 v[188:191], v150 offset:2048
	ds_read_b128 v[192:195], v150 offset:3072
	ds_read_b128 v[196:199], v150 offset:4096
	ds_read_b128 v[200:203], v150 offset:5120
	ds_read_b128 v[204:207], v150 offset:6144
	ds_read_b128 v[208:211], v150 offset:7168
	s_waitcnt vmcnt(8)
	s_waitcnt lgkmcnt(0)
	s_barrier
	s_setprio 1
	s_waitcnt lgkmcnt(0)
	v_mfma_f32_16x16x32_bf16 v[126:129], v[142:145], v[180:183], v[126:129]
	v_mfma_f32_16x16x32_bf16 v[122:125], v[156:159], v[180:183], v[122:125]
	v_mfma_f32_16x16x32_bf16 v[110:113], v[142:145], v[188:191], v[110:113]
	v_mfma_f32_16x16x32_bf16 v[106:109], v[156:159], v[188:191], v[106:109]
	v_mfma_f32_16x16x32_bf16 v[94:97], v[142:145], v[196:199], v[94:97]
	v_mfma_f32_16x16x32_bf16 v[90:93], v[156:159], v[196:199], v[90:93]
	v_mfma_f32_16x16x32_bf16 v[78:81], v[142:145], v[204:207], v[78:81]
	v_mfma_f32_16x16x32_bf16 v[74:77], v[156:159], v[204:207], v[74:77]
	v_mfma_f32_16x16x32_bf16 v[126:129], v[152:155], v[184:187], v[126:129]
	v_mfma_f32_16x16x32_bf16 v[122:125], v[160:163], v[184:187], v[122:125]
	v_mfma_f32_16x16x32_bf16 v[110:113], v[152:155], v[192:195], v[110:113]
	v_mfma_f32_16x16x32_bf16 v[106:109], v[160:163], v[192:195], v[106:109]
	v_mfma_f32_16x16x32_bf16 v[94:97], v[152:155], v[200:203], v[94:97]
	v_mfma_f32_16x16x32_bf16 v[90:93], v[160:163], v[200:203], v[90:93]
	v_mfma_f32_16x16x32_bf16 v[78:81], v[152:155], v[208:211], v[78:81]
	v_mfma_f32_16x16x32_bf16 v[74:77], v[160:163], v[208:211], v[74:77]
	s_setprio 0
	s_setprio 1
	v_mfma_f32_16x16x32_bf16 v[118:121], v[164:167], v[180:183], v[118:121]
	v_mfma_f32_16x16x32_bf16 v[114:117], v[172:175], v[180:183], v[114:117]
	v_mfma_f32_16x16x32_bf16 v[102:105], v[164:167], v[188:191], v[102:105]
	v_mfma_f32_16x16x32_bf16 v[98:101], v[172:175], v[188:191], v[98:101]
	v_mfma_f32_16x16x32_bf16 v[86:89], v[164:167], v[196:199], v[86:89]
	v_mfma_f32_16x16x32_bf16 v[82:85], v[172:175], v[196:199], v[82:85]
	v_mfma_f32_16x16x32_bf16 v[70:73], v[164:167], v[204:207], v[70:73]
	v_mfma_f32_16x16x32_bf16 v[66:69], v[172:175], v[204:207], v[66:69]
	v_mfma_f32_16x16x32_bf16 v[118:121], v[168:171], v[184:187], v[118:121]
	v_mfma_f32_16x16x32_bf16 v[114:117], v[176:179], v[184:187], v[114:117]
	v_mfma_f32_16x16x32_bf16 v[102:105], v[168:171], v[192:195], v[102:105]
	v_mfma_f32_16x16x32_bf16 v[98:101], v[176:179], v[192:195], v[98:101]
	v_mfma_f32_16x16x32_bf16 v[86:89], v[168:171], v[200:203], v[86:89]
	v_mfma_f32_16x16x32_bf16 v[82:85], v[176:179], v[200:203], v[82:85]
	v_mfma_f32_16x16x32_bf16 v[70:73], v[168:171], v[208:211], v[70:73]
	v_mfma_f32_16x16x32_bf16 v[66:69], v[176:179], v[208:211], v[66:69]
	s_setprio 0
	s_barrier
	s_add_i32 s24, s48, s37
	v_lshl_add_u64 v[212:213], s[28:29], 0, v[130:131]
	s_mov_b32 m0, s24
	s_nop 0
	global_load_lds_dwordx4 v[212:213], off
	s_add_i32 m0, s24, 0x2000
	s_add_u32 s24, s28, 0x80000
	v_lshl_add_u64 v[214:215], s[28:29], 0, v[132:133]
	s_addc_u32 s25, s29, 0
	s_add_i32 s56, s49, s37
	global_load_lds_dwordx4 v[214:215], off
	v_lshl_add_u64 v[216:217], s[24:25], 0, v[130:131]
	s_mov_b32 m0, s56
	v_lshl_add_u64 v[218:219], s[30:31], 0, v[132:133]
	global_load_lds_dwordx4 v[216:217], off
	v_lshl_add_u64 v[216:217], s[24:25], 0, v[132:133]
	s_add_i32 m0, s56, 0x2000
	s_nop 0
	global_load_lds_dwordx4 v[216:217], off
	v_lshl_add_u64 v[216:217], s[30:31], 0, v[130:131]
	s_mov_b32 m0, s5
	s_nop 0
	global_load_lds_dwordx4 v[216:217], off
	s_mov_b32 m0, s38
	s_nop 0
	global_load_lds_dwordx4 v[218:219], off
	ds_read_b128 v[180:183], v150 offset:16384
	ds_read_b128 v[184:187], v150 offset:17408
	ds_read_b128 v[188:191], v150 offset:18432
	ds_read_b128 v[192:195], v150 offset:19456
	ds_read_b128 v[196:199], v150 offset:20480
	ds_read_b128 v[200:203], v150 offset:21504
	ds_read_b128 v[204:207], v150 offset:22528
	ds_read_b128 v[208:211], v150 offset:23552
	s_waitcnt vmcnt(8)
	s_waitcnt lgkmcnt(0)
	s_barrier
	s_setprio 1
	s_waitcnt lgkmcnt(0)
	v_mfma_f32_16x16x32_bf16 v[62:65], v[142:145], v[180:183], v[62:65]
	v_mfma_f32_16x16x32_bf16 v[58:61], v[156:159], v[180:183], v[58:61]
	v_mfma_f32_16x16x32_bf16 v[46:49], v[142:145], v[188:191], v[46:49]
	v_mfma_f32_16x16x32_bf16 v[42:45], v[156:159], v[188:191], v[42:45]
	v_mfma_f32_16x16x32_bf16 v[30:33], v[142:145], v[196:199], v[30:33]
	v_mfma_f32_16x16x32_bf16 v[26:29], v[156:159], v[196:199], v[26:29]
	v_mfma_f32_16x16x32_bf16 v[14:17], v[142:145], v[204:207], v[14:17]
	v_mfma_f32_16x16x32_bf16 v[10:13], v[156:159], v[204:207], v[10:13]
	v_mfma_f32_16x16x32_bf16 v[62:65], v[152:155], v[184:187], v[62:65]
	v_mfma_f32_16x16x32_bf16 v[58:61], v[160:163], v[184:187], v[58:61]
	v_mfma_f32_16x16x32_bf16 v[46:49], v[152:155], v[192:195], v[46:49]
	v_mfma_f32_16x16x32_bf16 v[42:45], v[160:163], v[192:195], v[42:45]
	v_mfma_f32_16x16x32_bf16 v[30:33], v[152:155], v[200:203], v[30:33]
	v_mfma_f32_16x16x32_bf16 v[26:29], v[160:163], v[200:203], v[26:29]
	v_mfma_f32_16x16x32_bf16 v[14:17], v[152:155], v[208:211], v[14:17]
	v_mfma_f32_16x16x32_bf16 v[10:13], v[160:163], v[208:211], v[10:13]
	s_setprio 0
	s_setprio 1
	v_mfma_f32_16x16x32_bf16 v[54:57], v[164:167], v[180:183], v[54:57]
	v_mfma_f32_16x16x32_bf16 v[50:53], v[172:175], v[180:183], v[50:53]
	v_mfma_f32_16x16x32_bf16 v[38:41], v[164:167], v[188:191], v[38:41]
	v_mfma_f32_16x16x32_bf16 v[34:37], v[172:175], v[188:191], v[34:37]
	v_mfma_f32_16x16x32_bf16 v[22:25], v[164:167], v[196:199], v[22:25]
	v_mfma_f32_16x16x32_bf16 v[18:21], v[172:175], v[196:199], v[18:21]
	v_mfma_f32_16x16x32_bf16 v[6:9], v[164:167], v[204:207], v[6:9]
	v_mfma_f32_16x16x32_bf16 v[2:5], v[172:175], v[204:207], v[2:5]
	v_mfma_f32_16x16x32_bf16 v[54:57], v[168:171], v[184:187], v[54:57]
	v_mfma_f32_16x16x32_bf16 v[50:53], v[176:179], v[184:187], v[50:53]
	v_mfma_f32_16x16x32_bf16 v[38:41], v[168:171], v[192:195], v[38:41]
	v_mfma_f32_16x16x32_bf16 v[34:37], v[176:179], v[192:195], v[34:37]
	v_mfma_f32_16x16x32_bf16 v[22:25], v[168:171], v[200:203], v[22:25]
	v_mfma_f32_16x16x32_bf16 v[18:21], v[176:179], v[200:203], v[18:21]
	v_mfma_f32_16x16x32_bf16 v[6:9], v[168:171], v[208:211], v[6:9]
	v_mfma_f32_16x16x32_bf16 v[2:5], v[176:179], v[208:211], v[2:5]
	s_setprio 0
	s_barrier
	s_add_i32 s56, 0, 0x18000
	s_add_i32 s57, 0, 0x1c000
	s_add_u32 s24, s30, 0x80000
	s_addc_u32 s25, s31, 0
	s_mov_b32 m0, s39
	v_lshl_add_u64 v[220:221], s[24:25], 0, v[130:131]
	global_load_lds_dwordx4 v[220:221], off
	v_lshl_add_u64 v[220:221], s[24:25], 0, v[132:133]
	s_mov_b32 m0, s40
	s_nop 0
	global_load_lds_dwordx4 v[220:221], off
	v_add_u32_e32 v160, s56, v147
	v_add_u32_e32 v176, s57, v147
	ds_read_b128 v[142:145], v160
	ds_read_b128 v[152:155], v160 offset:1024
	ds_read_b128 v[156:159], v160 offset:2048
	ds_read_b128 v[160:163], v160 offset:3072
	ds_read_b128 v[164:167], v176
	ds_read_b128 v[168:171], v176 offset:1024
	ds_read_b128 v[172:175], v176 offset:2048
	ds_read_b128 v[176:179], v176 offset:3072
	ds_read_b128 v[180:183], v150 offset:32768
	ds_read_b128 v[184:187], v150 offset:33792
	ds_read_b128 v[188:191], v150 offset:34816
	ds_read_b128 v[192:195], v150 offset:35840
	ds_read_b128 v[196:199], v150 offset:36864
	ds_read_b128 v[200:203], v150 offset:37888
	ds_read_b128 v[204:207], v150 offset:38912
	ds_read_b128 v[208:211], v150 offset:39936
	s_waitcnt vmcnt(8)
	s_waitcnt lgkmcnt(0)
	s_barrier
	s_setprio 1
	s_waitcnt lgkmcnt(0)
	v_mfma_f32_16x16x32_bf16 v[126:129], v[142:145], v[180:183], v[126:129]
	v_mfma_f32_16x16x32_bf16 v[122:125], v[156:159], v[180:183], v[122:125]
	v_mfma_f32_16x16x32_bf16 v[110:113], v[142:145], v[188:191], v[110:113]
	v_mfma_f32_16x16x32_bf16 v[106:109], v[156:159], v[188:191], v[106:109]
	v_mfma_f32_16x16x32_bf16 v[94:97], v[142:145], v[196:199], v[94:97]
	v_mfma_f32_16x16x32_bf16 v[90:93], v[156:159], v[196:199], v[90:93]
	v_mfma_f32_16x16x32_bf16 v[78:81], v[142:145], v[204:207], v[78:81]
	v_mfma_f32_16x16x32_bf16 v[74:77], v[156:159], v[204:207], v[74:77]
	v_mfma_f32_16x16x32_bf16 v[126:129], v[152:155], v[184:187], v[126:129]
	v_mfma_f32_16x16x32_bf16 v[122:125], v[160:163], v[184:187], v[122:125]
	v_mfma_f32_16x16x32_bf16 v[110:113], v[152:155], v[192:195], v[110:113]
	v_mfma_f32_16x16x32_bf16 v[106:109], v[160:163], v[192:195], v[106:109]
	v_mfma_f32_16x16x32_bf16 v[94:97], v[152:155], v[200:203], v[94:97]
	v_mfma_f32_16x16x32_bf16 v[90:93], v[160:163], v[200:203], v[90:93]
	v_mfma_f32_16x16x32_bf16 v[78:81], v[152:155], v[208:211], v[78:81]
	v_mfma_f32_16x16x32_bf16 v[74:77], v[160:163], v[208:211], v[74:77]
	s_setprio 0
	s_setprio 1
	v_mfma_f32_16x16x32_bf16 v[118:121], v[164:167], v[180:183], v[118:121]
	v_mfma_f32_16x16x32_bf16 v[114:117], v[172:175], v[180:183], v[114:117]
	v_mfma_f32_16x16x32_bf16 v[102:105], v[164:167], v[188:191], v[102:105]
	v_mfma_f32_16x16x32_bf16 v[98:101], v[172:175], v[188:191], v[98:101]
	v_mfma_f32_16x16x32_bf16 v[86:89], v[164:167], v[196:199], v[86:89]
	v_mfma_f32_16x16x32_bf16 v[82:85], v[172:175], v[196:199], v[82:85]
	v_mfma_f32_16x16x32_bf16 v[70:73], v[164:167], v[204:207], v[70:73]
	v_mfma_f32_16x16x32_bf16 v[66:69], v[172:175], v[204:207], v[66:69]
	v_mfma_f32_16x16x32_bf16 v[118:121], v[168:171], v[184:187], v[118:121]
	v_mfma_f32_16x16x32_bf16 v[114:117], v[176:179], v[184:187], v[114:117]
	v_mfma_f32_16x16x32_bf16 v[102:105], v[168:171], v[192:195], v[102:105]
	v_mfma_f32_16x16x32_bf16 v[98:101], v[176:179], v[192:195], v[98:101]
	v_mfma_f32_16x16x32_bf16 v[86:89], v[168:171], v[200:203], v[86:89]
	v_mfma_f32_16x16x32_bf16 v[82:85], v[176:179], v[200:203], v[82:85]
	v_mfma_f32_16x16x32_bf16 v[70:73], v[168:171], v[208:211], v[70:73]
	v_mfma_f32_16x16x32_bf16 v[66:69], v[176:179], v[208:211], v[66:69]
	s_setprio 0
	s_barrier
	s_add_i32 s24, s56, s37
	v_lshl_add_u64 v[212:213], v[212:213], 0, s[12:13]
	s_mov_b32 m0, s24
	s_nop 0
	global_load_lds_dwordx4 v[212:213], off
	s_add_i32 m0, s24, 0x2000
	s_add_u32 s24, s28, 0x80080
	v_lshl_add_u64 v[212:213], v[214:215], 0, s[12:13]
	s_addc_u32 s25, s29, 0
	s_add_i32 s28, s57, s37
	global_load_lds_dwordx4 v[212:213], off
	v_lshl_add_u64 v[212:213], s[24:25], 0, v[130:131]
	s_mov_b32 m0, s28
	s_nop 0
	global_load_lds_dwordx4 v[212:213], off
	v_lshl_add_u64 v[212:213], s[24:25], 0, v[132:133]
	s_add_i32 m0, s28, 0x2000
	s_nop 0
	global_load_lds_dwordx4 v[212:213], off
	v_lshl_add_u64 v[212:213], v[216:217], 0, s[12:13]
	s_mov_b32 m0, s44
	s_nop 0
	global_load_lds_dwordx4 v[212:213], off
	v_lshl_add_u64 v[212:213], v[218:219], 0, s[12:13]
	s_mov_b32 m0, s45
	s_nop 0
	global_load_lds_dwordx4 v[212:213], off
	ds_read_b128 v[180:183], v150 offset:49152
	ds_read_b128 v[184:187], v150 offset:50176
	ds_read_b128 v[188:191], v150 offset:51200
	ds_read_b128 v[192:195], v150 offset:52224
	ds_read_b128 v[196:199], v150 offset:53248
	ds_read_b128 v[200:203], v150 offset:54272
	ds_read_b128 v[204:207], v150 offset:55296
	ds_read_b128 v[208:211], v150 offset:56320
	s_waitcnt vmcnt(8)
	s_waitcnt lgkmcnt(0)
	s_barrier
	s_setprio 1
	s_waitcnt lgkmcnt(0)
	v_mfma_f32_16x16x32_bf16 v[62:65], v[142:145], v[180:183], v[62:65]
	v_mfma_f32_16x16x32_bf16 v[58:61], v[156:159], v[180:183], v[58:61]
	v_mfma_f32_16x16x32_bf16 v[46:49], v[142:145], v[188:191], v[46:49]
	v_mfma_f32_16x16x32_bf16 v[42:45], v[156:159], v[188:191], v[42:45]
	v_mfma_f32_16x16x32_bf16 v[30:33], v[142:145], v[196:199], v[30:33]
	v_mfma_f32_16x16x32_bf16 v[26:29], v[156:159], v[196:199], v[26:29]
	v_mfma_f32_16x16x32_bf16 v[14:17], v[142:145], v[204:207], v[14:17]
	v_mfma_f32_16x16x32_bf16 v[10:13], v[156:159], v[204:207], v[10:13]
	v_mfma_f32_16x16x32_bf16 v[62:65], v[152:155], v[184:187], v[62:65]
	v_mfma_f32_16x16x32_bf16 v[58:61], v[160:163], v[184:187], v[58:61]
	v_mfma_f32_16x16x32_bf16 v[46:49], v[152:155], v[192:195], v[46:49]
	v_mfma_f32_16x16x32_bf16 v[42:45], v[160:163], v[192:195], v[42:45]
	v_mfma_f32_16x16x32_bf16 v[30:33], v[152:155], v[200:203], v[30:33]
	v_mfma_f32_16x16x32_bf16 v[26:29], v[160:163], v[200:203], v[26:29]
	v_mfma_f32_16x16x32_bf16 v[14:17], v[152:155], v[208:211], v[14:17]
	v_mfma_f32_16x16x32_bf16 v[10:13], v[160:163], v[208:211], v[10:13]
	s_setprio 0
	s_setprio 1
	v_mfma_f32_16x16x32_bf16 v[54:57], v[164:167], v[180:183], v[54:57]
	v_mfma_f32_16x16x32_bf16 v[50:53], v[172:175], v[180:183], v[50:53]
	v_mfma_f32_16x16x32_bf16 v[38:41], v[164:167], v[188:191], v[38:41]
	v_mfma_f32_16x16x32_bf16 v[34:37], v[172:175], v[188:191], v[34:37]
	v_mfma_f32_16x16x32_bf16 v[22:25], v[164:167], v[196:199], v[22:25]
	v_mfma_f32_16x16x32_bf16 v[18:21], v[172:175], v[196:199], v[18:21]
	v_mfma_f32_16x16x32_bf16 v[6:9], v[164:167], v[204:207], v[6:9]
	v_mfma_f32_16x16x32_bf16 v[2:5], v[172:175], v[204:207], v[2:5]
	v_mfma_f32_16x16x32_bf16 v[54:57], v[168:171], v[184:187], v[54:57]
	v_mfma_f32_16x16x32_bf16 v[50:53], v[176:179], v[184:187], v[50:53]
	v_mfma_f32_16x16x32_bf16 v[38:41], v[168:171], v[192:195], v[38:41]
	v_mfma_f32_16x16x32_bf16 v[34:37], v[176:179], v[192:195], v[34:37]
	v_mfma_f32_16x16x32_bf16 v[22:25], v[168:171], v[200:203], v[22:25]
	v_mfma_f32_16x16x32_bf16 v[18:21], v[176:179], v[200:203], v[18:21]
	v_mfma_f32_16x16x32_bf16 v[6:9], v[168:171], v[208:211], v[6:9]
	v_mfma_f32_16x16x32_bf16 v[2:5], v[176:179], v[208:211], v[2:5]
	s_setprio 0
	s_barrier
	s_add_i32 s55, s55, 2
	s_add_u32 s53, s53, 0x100
	s_addc_u32 s54, s54, 0
	s_cmp_gt_u32 s55, 29
	s_mov_b64 s[24:25], s[26:27]
	s_cbranch_scc0 .LBB0_3114
	s_and_b64 vcc, exec, s[14:15]
	s_cbranch_vccz .LBB0_3117
	s_barrier

.LBB0_3426:
	s_add_u32 s6, s40, 0x100
	s_addc_u32 s7, s41, 0
	s_cmpk_eq_i32 s68, 0x54
	s_cselect_b32 s45, s37, s7
	s_cselect_b32 s44, s36, s6
	s_cselect_b32 s43, s39, s67
	s_cselect_b32 s42, s38, s66
	v_lshl_add_u64 v[176:177], s[40:41], 0, v[132:133]
	s_add_i32 m0, s23, 0xc000
	s_nop 0
	global_load_lds_dwordx4 v[176:177], off
	v_lshl_add_u64 v[176:177], s[40:41], 0, v[134:135]
	s_add_i32 m0, s23, 0xe000
	s_nop 0
	global_load_lds_dwordx4 v[176:177], off
	ds_read_b128 v[140:143], v181
	ds_read_b128 v[144:147], v181 offset:1024
	ds_read_b128 v[148:151], v181 offset:2048
	ds_read_b128 v[152:155], v181 offset:3072
	ds_read_b128 v[156:159], v182
	ds_read_b128 v[160:163], v182 offset:1024
	ds_read_b128 v[164:167], v182 offset:2048
	ds_read_b128 v[168:171], v182 offset:3072
	ds_read_b128 v[172:175], v183
	ds_read_b128 v[186:189], v183 offset:1024
	ds_read_b128 v[190:193], v183 offset:2048
	ds_read_b128 v[194:197], v183 offset:3072
	ds_read_b128 v[198:201], v183 offset:4096
	ds_read_b128 v[202:205], v183 offset:5120
	ds_read_b128 v[206:209], v183 offset:6144
	ds_read_b128 v[210:213], v183 offset:7168
	s_waitcnt vmcnt(8)
	s_waitcnt lgkmcnt(0)
	s_barrier
	s_setprio 1
	s_waitcnt lgkmcnt(0)
	v_mfma_f32_16x16x32_bf16 v[124:127], v[140:143], v[172:175], v[124:127]
	v_mfma_f32_16x16x32_bf16 v[120:123], v[148:151], v[172:175], v[120:123]
	v_mfma_f32_16x16x32_bf16 v[108:111], v[140:143], v[190:193], v[108:111]
	v_mfma_f32_16x16x32_bf16 v[104:107], v[148:151], v[190:193], v[104:107]
	v_mfma_f32_16x16x32_bf16 v[92:95], v[140:143], v[198:201], v[92:95]
	v_mfma_f32_16x16x32_bf16 v[88:91], v[148:151], v[198:201], v[88:91]
	v_mfma_f32_16x16x32_bf16 v[76:79], v[140:143], v[206:209], v[76:79]
	v_mfma_f32_16x16x32_bf16 v[72:75], v[148:151], v[206:209], v[72:75]
	v_mfma_f32_16x16x32_bf16 v[124:127], v[144:147], v[186:189], v[124:127]
	v_mfma_f32_16x16x32_bf16 v[120:123], v[152:155], v[186:189], v[120:123]
	v_mfma_f32_16x16x32_bf16 v[108:111], v[144:147], v[194:197], v[108:111]
	v_mfma_f32_16x16x32_bf16 v[104:107], v[152:155], v[194:197], v[104:107]
	v_mfma_f32_16x16x32_bf16 v[92:95], v[144:147], v[202:205], v[92:95]
	v_mfma_f32_16x16x32_bf16 v[88:91], v[152:155], v[202:205], v[88:91]
	v_mfma_f32_16x16x32_bf16 v[76:79], v[144:147], v[210:213], v[76:79]
	v_mfma_f32_16x16x32_bf16 v[72:75], v[152:155], v[210:213], v[72:75]
	s_setprio 0
	s_setprio 1
	v_mfma_f32_16x16x32_bf16 v[116:119], v[156:159], v[172:175], v[116:119]
	v_mfma_f32_16x16x32_bf16 v[112:115], v[164:167], v[172:175], v[112:115]
	v_mfma_f32_16x16x32_bf16 v[100:103], v[156:159], v[190:193], v[100:103]
	v_mfma_f32_16x16x32_bf16 v[96:99], v[164:167], v[190:193], v[96:99]
	v_mfma_f32_16x16x32_bf16 v[84:87], v[156:159], v[198:201], v[84:87]
	v_mfma_f32_16x16x32_bf16 v[80:83], v[164:167], v[198:201], v[80:83]
	v_mfma_f32_16x16x32_bf16 v[68:71], v[156:159], v[206:209], v[68:71]
	v_mfma_f32_16x16x32_bf16 v[64:67], v[164:167], v[206:209], v[64:67]
	v_mfma_f32_16x16x32_bf16 v[116:119], v[160:163], v[186:189], v[116:119]
	v_mfma_f32_16x16x32_bf16 v[112:115], v[168:171], v[186:189], v[112:115]
	v_mfma_f32_16x16x32_bf16 v[100:103], v[160:163], v[194:197], v[100:103]
	v_mfma_f32_16x16x32_bf16 v[96:99], v[168:171], v[194:197], v[96:99]
	v_mfma_f32_16x16x32_bf16 v[84:87], v[160:163], v[202:205], v[84:87]
	v_mfma_f32_16x16x32_bf16 v[80:83], v[168:171], v[202:205], v[80:83]
	v_mfma_f32_16x16x32_bf16 v[68:71], v[160:163], v[210:213], v[68:71]
	v_mfma_f32_16x16x32_bf16 v[64:67], v[168:171], v[210:213], v[64:67]
	s_setprio 0
	s_barrier
	s_add_i32 s40, s59, s21
	v_lshl_add_u64 v[176:177], s[42:43], 0, v[128:129]
	s_mov_b32 m0, s40
	s_nop 0
	global_load_lds_dwordx4 v[176:177], off
	s_add_i32 m0, s40, 0x2000
	s_add_u32 s40, s42, 0x160000
	v_lshl_add_u64 v[214:215], s[42:43], 0, v[130:131]
	s_addc_u32 s41, s43, 0
	s_add_i32 s69, s60, s21
	global_load_lds_dwordx4 v[214:215], off
	v_lshl_add_u64 v[216:217], s[40:41], 0, v[128:129]
	s_mov_b32 m0, s69
	v_lshl_add_u64 v[218:219], s[44:45], 0, v[130:131]
	global_load_lds_dwordx4 v[216:217], off
	v_lshl_add_u64 v[216:217], s[40:41], 0, v[130:131]
	s_add_i32 m0, s69, 0x2000
	s_nop 0
	global_load_lds_dwordx4 v[216:217], off
	v_lshl_add_u64 v[216:217], s[44:45], 0, v[128:129]
	s_mov_b32 m0, s23
	s_nop 0
	global_load_lds_dwordx4 v[216:217], off
	s_mov_b32 m0, s47
	s_nop 0
	global_load_lds_dwordx4 v[218:219], off
	ds_read_b128 v[172:175], v183 offset:16384
	ds_read_b128 v[186:189], v183 offset:17408
	ds_read_b128 v[190:193], v183 offset:18432
	ds_read_b128 v[194:197], v183 offset:19456
	ds_read_b128 v[198:201], v183 offset:20480
	ds_read_b128 v[202:205], v183 offset:21504
	ds_read_b128 v[206:209], v183 offset:22528
	ds_read_b128 v[210:213], v183 offset:23552
	s_waitcnt vmcnt(8)
	s_waitcnt lgkmcnt(0)
	s_barrier
	s_setprio 1
	s_waitcnt lgkmcnt(0)
	v_mfma_f32_16x16x32_bf16 v[60:63], v[140:143], v[172:175], v[60:63]
	v_mfma_f32_16x16x32_bf16 v[56:59], v[148:151], v[172:175], v[56:59]
	v_mfma_f32_16x16x32_bf16 v[44:47], v[140:143], v[190:193], v[44:47]
	v_mfma_f32_16x16x32_bf16 v[40:43], v[148:151], v[190:193], v[40:43]
	v_mfma_f32_16x16x32_bf16 v[28:31], v[140:143], v[198:201], v[28:31]
	v_mfma_f32_16x16x32_bf16 v[24:27], v[148:151], v[198:201], v[24:27]
	v_mfma_f32_16x16x32_bf16 v[12:15], v[140:143], v[206:209], v[12:15]
	v_mfma_f32_16x16x32_bf16 v[8:11], v[148:151], v[206:209], v[8:11]
	v_mfma_f32_16x16x32_bf16 v[60:63], v[144:147], v[186:189], v[60:63]
	v_mfma_f32_16x16x32_bf16 v[56:59], v[152:155], v[186:189], v[56:59]
	v_mfma_f32_16x16x32_bf16 v[44:47], v[144:147], v[194:197], v[44:47]
	v_mfma_f32_16x16x32_bf16 v[40:43], v[152:155], v[194:197], v[40:43]
	v_mfma_f32_16x16x32_bf16 v[28:31], v[144:147], v[202:205], v[28:31]
	v_mfma_f32_16x16x32_bf16 v[24:27], v[152:155], v[202:205], v[24:27]
	v_mfma_f32_16x16x32_bf16 v[12:15], v[144:147], v[210:213], v[12:15]
	v_mfma_f32_16x16x32_bf16 v[8:11], v[152:155], v[210:213], v[8:11]
	s_setprio 0
	s_setprio 1
	v_mfma_f32_16x16x32_bf16 v[52:55], v[156:159], v[172:175], v[52:55]
	v_mfma_f32_16x16x32_bf16 v[48:51], v[164:167], v[172:175], v[48:51]
	v_mfma_f32_16x16x32_bf16 v[36:39], v[156:159], v[190:193], v[36:39]
	v_mfma_f32_16x16x32_bf16 v[32:35], v[164:167], v[190:193], v[32:35]
	v_mfma_f32_16x16x32_bf16 v[20:23], v[156:159], v[198:201], v[20:23]
	v_mfma_f32_16x16x32_bf16 v[16:19], v[164:167], v[198:201], v[16:19]
	v_mfma_f32_16x16x32_bf16 v[4:7], v[156:159], v[206:209], v[4:7]
	v_mfma_f32_16x16x32_bf16 v[0:3], v[164:167], v[206:209], v[0:3]
	v_mfma_f32_16x16x32_bf16 v[52:55], v[160:163], v[186:189], v[52:55]
	v_mfma_f32_16x16x32_bf16 v[48:51], v[168:171], v[186:189], v[48:51]
	v_mfma_f32_16x16x32_bf16 v[36:39], v[160:163], v[194:197], v[36:39]
	v_mfma_f32_16x16x32_bf16 v[32:35], v[168:171], v[194:197], v[32:35]
	v_mfma_f32_16x16x32_bf16 v[20:23], v[160:163], v[202:205], v[20:23]
	v_mfma_f32_16x16x32_bf16 v[16:19], v[168:171], v[202:205], v[16:19]
	v_mfma_f32_16x16x32_bf16 v[4:7], v[160:163], v[210:213], v[4:7]
	v_mfma_f32_16x16x32_bf16 v[0:3], v[168:171], v[210:213], v[0:3]
	s_setprio 0
	s_barrier
	s_add_i32 s69, 0, 0x18000
	s_add_i32 s70, 0, 0x1c000
	s_add_u32 s40, s44, 0x160000
	s_addc_u32 s41, s45, 0
	s_mov_b32 m0, s48
	v_lshl_add_u64 v[220:221], s[40:41], 0, v[128:129]
	global_load_lds_dwordx4 v[220:221], off
	v_lshl_add_u64 v[220:221], s[40:41], 0, v[130:131]
	s_mov_b32 m0, s49
	s_nop 0
	global_load_lds_dwordx4 v[220:221], off
	v_add_u32_e32 v152, s69, v180
	v_add_u32_e32 v168, s70, v180
	ds_read_b128 v[140:143], v152
	ds_read_b128 v[144:147], v152 offset:1024
	ds_read_b128 v[148:151], v152 offset:2048
	ds_read_b128 v[152:155], v152 offset:3072
	ds_read_b128 v[156:159], v168
	ds_read_b128 v[160:163], v168 offset:1024
	ds_read_b128 v[164:167], v168 offset:2048
	ds_read_b128 v[168:171], v168 offset:3072
	ds_read_b128 v[172:175], v183 offset:32768
	ds_read_b128 v[186:189], v183 offset:33792
	ds_read_b128 v[190:193], v183 offset:34816
	ds_read_b128 v[194:197], v183 offset:35840
	ds_read_b128 v[198:201], v183 offset:36864
	ds_read_b128 v[202:205], v183 offset:37888
	ds_read_b128 v[206:209], v183 offset:38912
	ds_read_b128 v[210:213], v183 offset:39936
	s_waitcnt vmcnt(8)
	s_waitcnt lgkmcnt(0)
	s_barrier
	s_setprio 1
	s_waitcnt lgkmcnt(0)
	v_mfma_f32_16x16x32_bf16 v[124:127], v[140:143], v[172:175], v[124:127]
	v_mfma_f32_16x16x32_bf16 v[120:123], v[148:151], v[172:175], v[120:123]
	v_mfma_f32_16x16x32_bf16 v[108:111], v[140:143], v[190:193], v[108:111]
	v_mfma_f32_16x16x32_bf16 v[104:107], v[148:151], v[190:193], v[104:107]
	v_mfma_f32_16x16x32_bf16 v[92:95], v[140:143], v[198:201], v[92:95]
	v_mfma_f32_16x16x32_bf16 v[88:91], v[148:151], v[198:201], v[88:91]
	v_mfma_f32_16x16x32_bf16 v[76:79], v[140:143], v[206:209], v[76:79]
	v_mfma_f32_16x16x32_bf16 v[72:75], v[148:151], v[206:209], v[72:75]
	v_mfma_f32_16x16x32_bf16 v[124:127], v[144:147], v[186:189], v[124:127]
	v_mfma_f32_16x16x32_bf16 v[120:123], v[152:155], v[186:189], v[120:123]
	v_mfma_f32_16x16x32_bf16 v[108:111], v[144:147], v[194:197], v[108:111]
	v_mfma_f32_16x16x32_bf16 v[104:107], v[152:155], v[194:197], v[104:107]
	v_mfma_f32_16x16x32_bf16 v[92:95], v[144:147], v[202:205], v[92:95]
	v_mfma_f32_16x16x32_bf16 v[88:91], v[152:155], v[202:205], v[88:91]
	v_mfma_f32_16x16x32_bf16 v[76:79], v[144:147], v[210:213], v[76:79]
	v_mfma_f32_16x16x32_bf16 v[72:75], v[152:155], v[210:213], v[72:75]
	s_setprio 0
	s_setprio 1
	v_mfma_f32_16x16x32_bf16 v[116:119], v[156:159], v[172:175], v[116:119]
	v_mfma_f32_16x16x32_bf16 v[112:115], v[164:167], v[172:175], v[112:115]
	v_mfma_f32_16x16x32_bf16 v[100:103], v[156:159], v[190:193], v[100:103]
	v_mfma_f32_16x16x32_bf16 v[96:99], v[164:167], v[190:193], v[96:99]
	v_mfma_f32_16x16x32_bf16 v[84:87], v[156:159], v[198:201], v[84:87]
	v_mfma_f32_16x16x32_bf16 v[80:83], v[164:167], v[198:201], v[80:83]
	v_mfma_f32_16x16x32_bf16 v[68:71], v[156:159], v[206:209], v[68:71]
	v_mfma_f32_16x16x32_bf16 v[64:67], v[164:167], v[206:209], v[64:67]
	v_mfma_f32_16x16x32_bf16 v[116:119], v[160:163], v[186:189], v[116:119]
	v_mfma_f32_16x16x32_bf16 v[112:115], v[168:171], v[186:189], v[112:115]
	v_mfma_f32_16x16x32_bf16 v[100:103], v[160:163], v[194:197], v[100:103]
	v_mfma_f32_16x16x32_bf16 v[96:99], v[168:171], v[194:197], v[96:99]
	v_mfma_f32_16x16x32_bf16 v[84:87], v[160:163], v[202:205], v[84:87]
	v_mfma_f32_16x16x32_bf16 v[80:83], v[168:171], v[202:205], v[80:83]
	v_mfma_f32_16x16x32_bf16 v[68:71], v[160:163], v[210:213], v[68:71]
	v_mfma_f32_16x16x32_bf16 v[64:67], v[168:171], v[210:213], v[64:67]
	s_setprio 0
	s_barrier
	s_add_i32 s40, s69, s21
	v_lshl_add_u64 v[176:177], v[176:177], 0, s[14:15]
	s_mov_b32 m0, s40
	s_nop 0
	global_load_lds_dwordx4 v[176:177], off
	s_add_i32 m0, s40, 0x2000
	s_add_u32 s40, s42, 0x160080
	v_lshl_add_u64 v[176:177], v[214:215], 0, s[14:15]
	s_addc_u32 s41, s43, 0
	s_add_i32 s42, s70, s21
	global_load_lds_dwordx4 v[176:177], off
	v_lshl_add_u64 v[176:177], s[40:41], 0, v[128:129]
	s_mov_b32 m0, s42
	s_nop 0
	global_load_lds_dwordx4 v[176:177], off
	v_lshl_add_u64 v[176:177], s[40:41], 0, v[130:131]
	s_add_i32 m0, s42, 0x2000
	s_nop 0
	global_load_lds_dwordx4 v[176:177], off
	v_lshl_add_u64 v[176:177], v[216:217], 0, s[14:15]
	s_mov_b32 m0, s56
	s_nop 0
	global_load_lds_dwordx4 v[176:177], off
	v_lshl_add_u64 v[176:177], v[218:219], 0, s[14:15]
	s_mov_b32 m0, s57
	s_nop 0
	global_load_lds_dwordx4 v[176:177], off
	ds_read_b128 v[172:175], v183 offset:49152
	ds_read_b128 v[186:189], v183 offset:50176
	ds_read_b128 v[190:193], v183 offset:51200
	ds_read_b128 v[194:197], v183 offset:52224
	ds_read_b128 v[198:201], v183 offset:53248
	ds_read_b128 v[202:205], v183 offset:54272
	ds_read_b128 v[206:209], v183 offset:55296
	ds_read_b128 v[210:213], v183 offset:56320
	s_waitcnt vmcnt(8)
	s_waitcnt lgkmcnt(0)
	s_barrier
	s_setprio 1
	s_waitcnt lgkmcnt(0)
	v_mfma_f32_16x16x32_bf16 v[60:63], v[140:143], v[172:175], v[60:63]
	v_mfma_f32_16x16x32_bf16 v[56:59], v[148:151], v[172:175], v[56:59]
	v_mfma_f32_16x16x32_bf16 v[44:47], v[140:143], v[190:193], v[44:47]
	v_mfma_f32_16x16x32_bf16 v[40:43], v[148:151], v[190:193], v[40:43]
	v_mfma_f32_16x16x32_bf16 v[28:31], v[140:143], v[198:201], v[28:31]
	v_mfma_f32_16x16x32_bf16 v[24:27], v[148:151], v[198:201], v[24:27]
	v_mfma_f32_16x16x32_bf16 v[12:15], v[140:143], v[206:209], v[12:15]
	v_mfma_f32_16x16x32_bf16 v[8:11], v[148:151], v[206:209], v[8:11]
	v_mfma_f32_16x16x32_bf16 v[60:63], v[144:147], v[186:189], v[60:63]
	v_mfma_f32_16x16x32_bf16 v[56:59], v[152:155], v[186:189], v[56:59]
	v_mfma_f32_16x16x32_bf16 v[44:47], v[144:147], v[194:197], v[44:47]
	v_mfma_f32_16x16x32_bf16 v[40:43], v[152:155], v[194:197], v[40:43]
	v_mfma_f32_16x16x32_bf16 v[28:31], v[144:147], v[202:205], v[28:31]
	v_mfma_f32_16x16x32_bf16 v[24:27], v[152:155], v[202:205], v[24:27]
	v_mfma_f32_16x16x32_bf16 v[12:15], v[144:147], v[210:213], v[12:15]
	v_mfma_f32_16x16x32_bf16 v[8:11], v[152:155], v[210:213], v[8:11]
	s_setprio 0
	s_setprio 1
	v_mfma_f32_16x16x32_bf16 v[52:55], v[156:159], v[172:175], v[52:55]
	v_mfma_f32_16x16x32_bf16 v[48:51], v[164:167], v[172:175], v[48:51]
	v_mfma_f32_16x16x32_bf16 v[36:39], v[156:159], v[190:193], v[36:39]
	v_mfma_f32_16x16x32_bf16 v[32:35], v[164:167], v[190:193], v[32:35]
	v_mfma_f32_16x16x32_bf16 v[20:23], v[156:159], v[198:201], v[20:23]
	v_mfma_f32_16x16x32_bf16 v[16:19], v[164:167], v[198:201], v[16:19]
	v_mfma_f32_16x16x32_bf16 v[4:7], v[156:159], v[206:209], v[4:7]
	v_mfma_f32_16x16x32_bf16 v[0:3], v[164:167], v[206:209], v[0:3]
	v_mfma_f32_16x16x32_bf16 v[52:55], v[160:163], v[186:189], v[52:55]
	v_mfma_f32_16x16x32_bf16 v[48:51], v[168:171], v[186:189], v[48:51]
	v_mfma_f32_16x16x32_bf16 v[36:39], v[160:163], v[194:197], v[36:39]
	v_mfma_f32_16x16x32_bf16 v[32:35], v[168:171], v[194:197], v[32:35]
	v_mfma_f32_16x16x32_bf16 v[20:23], v[160:163], v[202:205], v[20:23]
	v_mfma_f32_16x16x32_bf16 v[16:19], v[168:171], v[202:205], v[16:19]
	v_mfma_f32_16x16x32_bf16 v[4:7], v[160:163], v[210:213], v[4:7]
	v_mfma_f32_16x16x32_bf16 v[0:3], v[168:171], v[210:213], v[0:3]
	s_setprio 0
	s_barrier
	s_add_i32 s68, s68, 2
	s_add_u32 s66, s66, 0x100
	s_addc_u32 s67, s67, 0
	s_cmpk_gt_u32 s68, 0x55
	s_mov_b64 s[40:41], s[6:7]
	s_cbranch_scc0 .LBB0_3426
	s_and_b64 vcc, exec, s[18:19]
	s_cbranch_vccz .LBB0_3429
	s_barrier
